# gMLP group loop: spatial-weight tile, gate tile u and bias loads all issued at the top of the group staging instead of one at a time behind vmcnt(0)
# speedup vs baseline: 1.0191x; 1.0097x over previous
; __device__ __forceinline__ float bf2f(unsigned h) { return __uint_as_float(h << 16); }
; __device__ __forceinline__ unsigned cvt2(float lo, float hi) { bf16v2_t r = __builtin_convertvector((f32x2){lo, hi}, bf16v2_t); return __builtin_bit_cast(unsigned, r); }
; __device__ __forceinline__ float gelu_(float x) { return x * sigm_(1.5957691216f * (x + 0.044715f * x * x * x)); }
; __device__ __forceinline__ void gmlp_mfma(LAS unsigned char* lds, const unsigned char* R, bf16_t* O, const float* lng, const float* lnb, const float* wsp, const float* bsp, int unit, int tid) {
;     ...
;         const int t = 16 * w + fr; const float bt = bsp[g * 128 + t];
; #pragma unroll
;         for (int ct = 0; ct < 8; ++ct) { const int c0 = g * 128 + 16 * ct + 4 * fq; const u32x2 uu = *(const u32x2*)(U + (r0 + t) * AW + c0);
;             u32x2 o; o.x = cvt2(gelu_(bf2f(uu.x & 0xffff)) * (acc[ct][0] + bt), gelu_(bf2f(uu.x >> 16)) * (acc[ct][1] + bt));
;             o.y = cvt2(gelu_(bf2f(uu.y & 0xffff)) * (acc[ct][2] + bt), gelu_(bf2f(uu.y >> 16)) * (acc[ct][3] + bt));
;             *(u32x2*)(O + (r0 + t) * D + 512 + c0) = o; }
.LBB0_150:
	v_add_u32_e32 v64, s36, v56
	v_ashrrev_i32_e32 v65, 31, v64
	v_or_b32_e32 v0, s36, v69
	v_lshl_add_u64 v[64:65], v[64:65], 2, s[30:31]
	v_lshlrev_b32_e32 v0, 1, v0
	v_mov_b32_e32 v62, v148
	v_lshl_add_u64 v[64:65], v[58:59], 0, v[0:1]
	v_mov_b32_e32 v66, v96
	v_mov_b32_e32 v67, v97
	s_add_i32 s41, s41, 1
	s_cmp_eq_u32 s41, 4
	s_waitcnt vmcnt(1)
	v_pk_add_f32 v[36:37], v[62:63], v[36:37] op_sel_hi:[0,1]
	v_pk_add_f32 v[38:39], v[62:63], v[38:39] op_sel_hi:[0,1]
	s_waitcnt vmcnt(0)
	v_lshlrev_b32_e32 v92, 16, v66
	v_mul_f32_e32 v57, 0x3d372713, v92
	v_and_b32_e32 v93, 0xffff0000, v66
	v_mul_f32_e32 v57, v57, v92
	v_mov_b32_e32 v66, v92
	v_fmac_f32_e32 v66, v57, v66
	v_mul_f32_e32 v57, 0x3fcc422a, v66
	v_mul_f32_e32 v57, 0xbfb8aa3b, v57
	v_exp_f32_e32 v57, v57
	v_mov_b32_e32 v66, v93
	v_pk_add_f32 v[32:33], v[62:63], v[32:33] op_sel_hi:[0,1]
	v_pk_add_f32 v[34:35], v[62:63], v[34:35] op_sel_hi:[0,1]
	v_add_f32_e32 v57, 1.0, v57
	v_rcp_f32_e32 v94, v57
	v_mul_f32_e32 v57, 0x3d372713, v93
	v_mul_f32_e32 v57, v57, v93
	v_fmac_f32_e32 v66, v57, v66
	v_mul_f32_e32 v57, 0x3fcc422a, v66
	v_mul_f32_e32 v57, 0xbfb8aa3b, v57
	v_exp_f32_e32 v57, v57
	v_pk_add_f32 v[28:29], v[62:63], v[28:29] op_sel_hi:[0,1]
	v_pk_add_f32 v[30:31], v[62:63], v[30:31] op_sel_hi:[0,1]
	v_pk_add_f32 v[24:25], v[62:63], v[24:25] op_sel_hi:[0,1]
	v_add_f32_e32 v57, 1.0, v57
	v_rcp_f32_e32 v95, v57
	v_pk_add_f32 v[26:27], v[62:63], v[26:27] op_sel_hi:[0,1]
	v_pk_add_f32 v[20:21], v[62:63], v[20:21] op_sel_hi:[0,1]
	v_pk_add_f32 v[22:23], v[62:63], v[22:23] op_sel_hi:[0,1]
	v_pk_mul_f32 v[92:93], v[94:95], v[92:93]
	v_pk_add_f32 v[16:17], v[62:63], v[16:17] op_sel_hi:[0,1]
	v_pk_mul_f32 v[36:37], v[36:37], v[92:93]
	v_pk_add_f32 v[18:19], v[62:63], v[18:19] op_sel_hi:[0,1]
	v_cvt_pk_bf16_f32 v66, v36, v37
	v_lshlrev_b32_e32 v36, 16, v67
	v_mul_f32_e32 v57, 0x3d372713, v36
	v_and_b32_e32 v37, 0xffff0000, v67
	v_mul_f32_e32 v57, v57, v36
	v_mov_b32_e32 v67, v36
	v_fmac_f32_e32 v67, v57, v67
	v_mul_f32_e32 v57, 0x3fcc422a, v67
	v_mul_f32_e32 v57, 0xbfb8aa3b, v57
	v_exp_f32_e32 v57, v57
	v_mov_b32_e32 v67, v37
	v_pk_add_f32 v[12:13], v[62:63], v[12:13] op_sel_hi:[0,1]
	v_pk_add_f32 v[14:15], v[62:63], v[14:15] op_sel_hi:[0,1]
	v_add_f32_e32 v57, 1.0, v57
	v_rcp_f32_e32 v92, v57
	v_mul_f32_e32 v57, 0x3d372713, v37
	v_mul_f32_e32 v57, v57, v37
	v_fmac_f32_e32 v67, v57, v67
	v_mul_f32_e32 v57, 0x3fcc422a, v67
	v_mul_f32_e32 v57, 0xbfb8aa3b, v57
	v_exp_f32_e32 v57, v57
	v_pk_add_f32 v[8:9], v[62:63], v[8:9] op_sel_hi:[0,1]
	v_pk_add_f32 v[10:11], v[62:63], v[10:11] op_sel_hi:[0,1]
	v_add_f32_e32 v57, 1.0, v57
	v_rcp_f32_e32 v93, v57
	s_nop 0
	v_pk_mul_f32 v[36:37], v[92:93], v[36:37]
	s_nop 0
	v_pk_mul_f32 v[36:37], v[38:39], v[36:37]
	s_nop 0
	v_cvt_pk_bf16_f32 v67, v36, v37
	v_lshl_add_u64 v[36:37], v[60:61], 0, v[0:1]
	global_store_dwordx2 v[36:37], v[66:67], off offset:1024
	v_mov_b32_e32 v38, v98
	v_mov_b32_e32 v39, v99
	v_lshlrev_b32_e32 v66, 16, v38
	v_mul_f32_e32 v0, 0x3d372713, v66
	v_and_b32_e32 v67, 0xffff0000, v38
	v_mul_f32_e32 v0, v0, v66
	v_mov_b32_e32 v38, v66
	v_fmac_f32_e32 v38, v0, v38
	v_mul_f32_e32 v0, 0x3fcc422a, v38
	v_mul_f32_e32 v0, 0xbfb8aa3b, v0
	v_exp_f32_e32 v0, v0
	v_mov_b32_e32 v38, v67
	v_add_f32_e32 v0, 1.0, v0
	v_rcp_f32_e32 v92, v0
	v_mul_f32_e32 v0, 0x3d372713, v67
	v_mul_f32_e32 v0, v0, v67
	v_fmac_f32_e32 v38, v0, v38
	v_mul_f32_e32 v0, 0x3fcc422a, v38
	v_mul_f32_e32 v0, 0xbfb8aa3b, v0
	v_exp_f32_e32 v0, v0
	v_lshlrev_b32_e32 v38, 16, v39
	v_and_b32_e32 v39, 0xffff0000, v39
	v_add_f32_e32 v0, 1.0, v0
	v_rcp_f32_e32 v93, v0
	v_mul_f32_e32 v0, 0x3d372713, v38
	v_mul_f32_e32 v0, v0, v38
	v_pk_mul_f32 v[66:67], v[92:93], v[66:67]
	s_nop 0
	v_pk_mul_f32 v[32:33], v[32:33], v[66:67]
	s_nop 0
	v_cvt_pk_bf16_f32 v32, v32, v33
	v_mov_b32_e32 v33, v38
	v_fmac_f32_e32 v33, v0, v33
	v_mul_f32_e32 v0, 0x3fcc422a, v33
	v_mul_f32_e32 v0, 0xbfb8aa3b, v0
	v_exp_f32_e32 v0, v0
	v_mov_b32_e32 v33, v39
	v_add_f32_e32 v0, 1.0, v0
	v_rcp_f32_e32 v66, v0
	v_mul_f32_e32 v0, 0x3d372713, v39
	v_mul_f32_e32 v0, v0, v39
	v_fmac_f32_e32 v33, v0, v33
	v_mul_f32_e32 v0, 0x3fcc422a, v33
	v_mul_f32_e32 v0, 0xbfb8aa3b, v0
	v_exp_f32_e32 v0, v0
	s_nop 0
	v_add_f32_e32 v0, 1.0, v0
	v_rcp_f32_e32 v67, v0
	s_nop 0
	v_pk_mul_f32 v[38:39], v[66:67], v[38:39]
	s_nop 0
	v_pk_mul_f32 v[34:35], v[34:35], v[38:39]
	s_nop 0
	v_cvt_pk_bf16_f32 v33, v34, v35
	global_store_dwordx2 v[36:37], v[32:33], off offset:1056
	v_mov_b32_e32 v32, v100
	v_mov_b32_e32 v33, v101
	v_lshlrev_b32_e32 v34, 16, v32
	v_mul_f32_e32 v0, 0x3d372713, v34
	v_and_b32_e32 v35, 0xffff0000, v32
	v_mul_f32_e32 v0, v0, v34
	v_mov_b32_e32 v32, v34
	v_fmac_f32_e32 v32, v0, v32
	v_mul_f32_e32 v0, 0x3fcc422a, v32
	v_mul_f32_e32 v0, 0xbfb8aa3b, v0
	v_exp_f32_e32 v0, v0
	v_mov_b32_e32 v32, v35
	v_add_f32_e32 v0, 1.0, v0
	v_rcp_f32_e32 v38, v0
	v_mul_f32_e32 v0, 0x3d372713, v35
	v_mul_f32_e32 v0, v0, v35
	v_fmac_f32_e32 v32, v0, v32
	v_mul_f32_e32 v0, 0x3fcc422a, v32
	v_mul_f32_e32 v0, 0xbfb8aa3b, v0
	v_exp_f32_e32 v0, v0
	v_lshlrev_b32_e32 v32, 16, v33
	v_and_b32_e32 v33, 0xffff0000, v33
	v_add_f32_e32 v0, 1.0, v0
	v_rcp_f32_e32 v39, v0
	v_mul_f32_e32 v0, 0x3d372713, v32
	v_mul_f32_e32 v0, v0, v32
	v_pk_mul_f32 v[34:35], v[38:39], v[34:35]
	s_nop 0
	v_pk_mul_f32 v[28:29], v[28:29], v[34:35]
	s_nop 0
	v_cvt_pk_bf16_f32 v28, v28, v29
	v_mov_b32_e32 v29, v32
	v_fmac_f32_e32 v29, v0, v29
	v_mul_f32_e32 v0, 0x3fcc422a, v29
	v_mul_f32_e32 v0, 0xbfb8aa3b, v0
	v_exp_f32_e32 v0, v0
	v_mov_b32_e32 v29, v33
	v_add_f32_e32 v0, 1.0, v0
	v_rcp_f32_e32 v34, v0
	v_mul_f32_e32 v0, 0x3d372713, v33
	v_mul_f32_e32 v0, v0, v33
; __device__ __forceinline__ float bf2f(unsigned h) { return __uint_as_float(h << 16); }
; __device__ __forceinline__ unsigned cvt2(float lo, float hi) { bf16v2_t r = __builtin_convertvector((f32x2){lo, hi}, bf16v2_t); return __builtin_bit_cast(unsigned, r); }
; __device__ __forceinline__ float gelu_(float x) { return x * sigm_(1.5957691216f * (x + 0.044715f * x * x * x)); }
; __device__ __forceinline__ void gmlp_mfma(LAS unsigned char* lds, const unsigned char* R, bf16_t* O, const float* lng, const float* lnb, const float* wsp, const float* bsp, int unit, int tid) {
;     ...
;         for (int ct = 0; ct < 8; ++ct) { const int c0 = g * 128 + 16 * ct + 4 * fq; const u32x2 uu = *(const u32x2*)(U + (r0 + t) * AW + c0);
;             u32x2 o; o.x = cvt2(gelu_(bf2f(uu.x & 0xffff)) * (acc[ct][0] + bt), gelu_(bf2f(uu.x >> 16)) * (acc[ct][1] + bt));
;             o.y = cvt2(gelu_(bf2f(uu.y & 0xffff)) * (acc[ct][2] + bt), gelu_(bf2f(uu.y >> 16)) * (acc[ct][3] + bt));
;             *(u32x2*)(O + (r0 + t) * D + 512 + c0) = o; }
	v_fmac_f32_e32 v29, v0, v29
	v_mul_f32_e32 v0, 0x3fcc422a, v29
	v_mul_f32_e32 v0, 0xbfb8aa3b, v0
	v_exp_f32_e32 v0, v0
	s_nop 0
	v_add_f32_e32 v0, 1.0, v0
	v_rcp_f32_e32 v35, v0
	s_nop 0
	v_pk_mul_f32 v[32:33], v[34:35], v[32:33]
	s_nop 0
	v_pk_mul_f32 v[30:31], v[30:31], v[32:33]
	s_nop 0
	v_cvt_pk_bf16_f32 v29, v30, v31
	global_store_dwordx2 v[36:37], v[28:29], off offset:1088
	v_mov_b32_e32 v28, v102
	v_mov_b32_e32 v29, v103
	v_lshlrev_b32_e32 v30, 16, v28
	v_mul_f32_e32 v0, 0x3d372713, v30
	v_and_b32_e32 v31, 0xffff0000, v28
	v_mul_f32_e32 v0, v0, v30
	v_mov_b32_e32 v28, v30
	v_fmac_f32_e32 v28, v0, v28
	v_mul_f32_e32 v0, 0x3fcc422a, v28
	v_mul_f32_e32 v0, 0xbfb8aa3b, v0
	v_exp_f32_e32 v0, v0
	v_mov_b32_e32 v28, v31
	v_add_f32_e32 v0, 1.0, v0
	v_rcp_f32_e32 v32, v0
	v_mul_f32_e32 v0, 0x3d372713, v31
	v_mul_f32_e32 v0, v0, v31
	v_fmac_f32_e32 v28, v0, v28
	v_mul_f32_e32 v0, 0x3fcc422a, v28
	v_mul_f32_e32 v0, 0xbfb8aa3b, v0
	v_exp_f32_e32 v0, v0
	v_lshlrev_b32_e32 v28, 16, v29
	v_and_b32_e32 v29, 0xffff0000, v29
	v_add_f32_e32 v0, 1.0, v0
	v_rcp_f32_e32 v33, v0
	v_mul_f32_e32 v0, 0x3d372713, v28
	v_mul_f32_e32 v0, v0, v28
	v_pk_mul_f32 v[30:31], v[32:33], v[30:31]
	s_nop 0
	v_pk_mul_f32 v[24:25], v[24:25], v[30:31]
	s_nop 0
	v_cvt_pk_bf16_f32 v24, v24, v25
	v_mov_b32_e32 v25, v28
	v_fmac_f32_e32 v25, v0, v25
	v_mul_f32_e32 v0, 0x3fcc422a, v25
	v_mul_f32_e32 v0, 0xbfb8aa3b, v0
	v_exp_f32_e32 v0, v0
	v_mov_b32_e32 v25, v29
	v_add_f32_e32 v0, 1.0, v0
	v_rcp_f32_e32 v30, v0
	v_mul_f32_e32 v0, 0x3d372713, v29
	v_mul_f32_e32 v0, v0, v29
	v_fmac_f32_e32 v25, v0, v25
	v_mul_f32_e32 v0, 0x3fcc422a, v25
	v_mul_f32_e32 v0, 0xbfb8aa3b, v0
	v_exp_f32_e32 v0, v0
	s_nop 0
	v_add_f32_e32 v0, 1.0, v0
	v_rcp_f32_e32 v31, v0
	s_nop 0
	v_pk_mul_f32 v[28:29], v[30:31], v[28:29]
	s_nop 0
	v_pk_mul_f32 v[26:27], v[26:27], v[28:29]
	s_nop 0
	v_cvt_pk_bf16_f32 v25, v26, v27
	global_store_dwordx2 v[36:37], v[24:25], off offset:1120
	v_mov_b32_e32 v24, v104
	v_mov_b32_e32 v25, v105
	v_lshlrev_b32_e32 v26, 16, v24
	v_mul_f32_e32 v0, 0x3d372713, v26
	v_and_b32_e32 v27, 0xffff0000, v24
	v_mul_f32_e32 v0, v0, v26
	v_mov_b32_e32 v24, v26
	v_fmac_f32_e32 v24, v0, v24
	v_mul_f32_e32 v0, 0x3fcc422a, v24
	v_mul_f32_e32 v0, 0xbfb8aa3b, v0
	v_exp_f32_e32 v0, v0
	v_mov_b32_e32 v24, v27
	v_add_f32_e32 v0, 1.0, v0
	v_rcp_f32_e32 v28, v0
	v_mul_f32_e32 v0, 0x3d372713, v27
	v_mul_f32_e32 v0, v0, v27
	v_fmac_f32_e32 v24, v0, v24
	v_mul_f32_e32 v0, 0x3fcc422a, v24
	v_mul_f32_e32 v0, 0xbfb8aa3b, v0
	v_exp_f32_e32 v0, v0
	v_lshlrev_b32_e32 v24, 16, v25
	v_and_b32_e32 v25, 0xffff0000, v25
	v_add_f32_e32 v0, 1.0, v0
	v_rcp_f32_e32 v29, v0
	v_mul_f32_e32 v0, 0x3d372713, v24
	v_mul_f32_e32 v0, v0, v24
	v_pk_mul_f32 v[26:27], v[28:29], v[26:27]
	s_nop 0
	v_pk_mul_f32 v[20:21], v[20:21], v[26:27]
	s_nop 0
	v_cvt_pk_bf16_f32 v20, v20, v21
	v_mov_b32_e32 v21, v24
	v_fmac_f32_e32 v21, v0, v21
	v_mul_f32_e32 v0, 0x3fcc422a, v21
	v_mul_f32_e32 v0, 0xbfb8aa3b, v0
	v_exp_f32_e32 v0, v0
	v_mov_b32_e32 v21, v25
	v_add_f32_e32 v0, 1.0, v0
	v_rcp_f32_e32 v26, v0
	v_mul_f32_e32 v0, 0x3d372713, v25
	v_mul_f32_e32 v0, v0, v25
	v_fmac_f32_e32 v21, v0, v21
	v_mul_f32_e32 v0, 0x3fcc422a, v21
	v_mul_f32_e32 v0, 0xbfb8aa3b, v0
	v_exp_f32_e32 v0, v0
	s_nop 0
	v_add_f32_e32 v0, 1.0, v0
	v_rcp_f32_e32 v27, v0
	s_nop 0
	v_pk_mul_f32 v[24:25], v[26:27], v[24:25]
	s_nop 0
	v_pk_mul_f32 v[22:23], v[22:23], v[24:25]
	s_nop 0
	v_cvt_pk_bf16_f32 v21, v22, v23
	global_store_dwordx2 v[36:37], v[20:21], off offset:1152
	v_mov_b32_e32 v20, v106
	v_mov_b32_e32 v21, v107
	v_lshlrev_b32_e32 v22, 16, v20
	v_mul_f32_e32 v0, 0x3d372713, v22
	v_and_b32_e32 v23, 0xffff0000, v20
	v_mul_f32_e32 v0, v0, v22
	v_mov_b32_e32 v20, v22
	v_fmac_f32_e32 v20, v0, v20
	v_mul_f32_e32 v0, 0x3fcc422a, v20
	v_mul_f32_e32 v0, 0xbfb8aa3b, v0
	v_exp_f32_e32 v0, v0
	v_mov_b32_e32 v20, v23
	v_add_f32_e32 v0, 1.0, v0
	v_rcp_f32_e32 v24, v0
	v_mul_f32_e32 v0, 0x3d372713, v23
	v_mul_f32_e32 v0, v0, v23
	v_fmac_f32_e32 v20, v0, v20
	v_mul_f32_e32 v0, 0x3fcc422a, v20
	v_mul_f32_e32 v0, 0xbfb8aa3b, v0
	v_exp_f32_e32 v0, v0
	v_lshlrev_b32_e32 v20, 16, v21
	v_and_b32_e32 v21, 0xffff0000, v21
	v_add_f32_e32 v0, 1.0, v0
	v_rcp_f32_e32 v25, v0
	v_mul_f32_e32 v0, 0x3d372713, v20
	v_mul_f32_e32 v0, v0, v20
	v_pk_mul_f32 v[22:23], v[24:25], v[22:23]
	s_nop 0
	v_pk_mul_f32 v[16:17], v[16:17], v[22:23]
	s_nop 0
	v_cvt_pk_bf16_f32 v16, v16, v17
	v_mov_b32_e32 v17, v20
	v_fmac_f32_e32 v17, v0, v17
	v_mul_f32_e32 v0, 0x3fcc422a, v17
	v_mul_f32_e32 v0, 0xbfb8aa3b, v0
	v_exp_f32_e32 v0, v0
	v_mov_b32_e32 v17, v21
	v_add_f32_e32 v0, 1.0, v0
	v_rcp_f32_e32 v22, v0
	v_mul_f32_e32 v0, 0x3d372713, v21
	v_mul_f32_e32 v0, v0, v21
	v_fmac_f32_e32 v17, v0, v17
	v_mul_f32_e32 v0, 0x3fcc422a, v17
	v_mul_f32_e32 v0, 0xbfb8aa3b, v0
	v_exp_f32_e32 v0, v0
	s_nop 0
	v_add_f32_e32 v0, 1.0, v0
	v_rcp_f32_e32 v23, v0
	s_nop 0
	v_pk_mul_f32 v[20:21], v[22:23], v[20:21]
	s_nop 0
	v_pk_mul_f32 v[18:19], v[18:19], v[20:21]
	s_nop 0
	v_cvt_pk_bf16_f32 v17, v18, v19
	global_store_dwordx2 v[36:37], v[16:17], off offset:1184
	v_mov_b32_e32 v16, v108
	v_mov_b32_e32 v17, v109
	v_lshlrev_b32_e32 v18, 16, v16
	v_mul_f32_e32 v0, 0x3d372713, v18
	v_and_b32_e32 v19, 0xffff0000, v16
	v_mul_f32_e32 v0, v0, v18
	v_mov_b32_e32 v16, v18
	v_fmac_f32_e32 v16, v0, v16
	v_mul_f32_e32 v0, 0x3fcc422a, v16
	v_mul_f32_e32 v0, 0xbfb8aa3b, v0
	v_exp_f32_e32 v0, v0
	v_mov_b32_e32 v16, v19
	v_add_f32_e32 v0, 1.0, v0
	v_rcp_f32_e32 v20, v0
	v_mul_f32_e32 v0, 0x3d372713, v19
	v_mul_f32_e32 v0, v0, v19
	v_fmac_f32_e32 v16, v0, v16
	v_mul_f32_e32 v0, 0x3fcc422a, v16
	v_mul_f32_e32 v0, 0xbfb8aa3b, v0
	v_exp_f32_e32 v0, v0
; #define LAS __attribute__((address_space(3)))
; __device__ __forceinline__ float bf2f(unsigned h) { return __uint_as_float(h << 16); }
; #define MFMA16(a, b, c) __builtin_amdgcn_mfma_f32_16x16x32_bf16(a, b, c, 0, 0, 0)
; __device__ __forceinline__ unsigned cvt2(float lo, float hi) { bf16v2_t r = __builtin_convertvector((f32x2){lo, hi}, bf16v2_t); return __builtin_bit_cast(unsigned, r); }
; __device__ __forceinline__ void gmlp_mfma(LAS unsigned char* lds, const unsigned char* R, bf16_t* O, const float* lng, const float* lnb, const float* wsp, const float* bsp, int unit, int tid) {
;     ...
;         for (int i = 0; i < 4; ++i) { const int idx = tid + 512 * i, s = idx & 127, ch = idx >> 7;
;             const u32x4 x4 = *(const u32x4*)(VV + (r0 + s) * AW + g * 128 + ch * 8);
;             const f32x4 ga = *(const f32x4*)(lng + g * 128 + ch * 8), gb = *(const f32x4*)(lng + g * 128 + ch * 8 + 4), ba = *(const f32x4*)(lnb + g * 128 + ch * 8), bb = *(const f32x4*)(lnb + g * 128 + ch * 8 + 4);
;     ...
;         for (int i = 0; i < 8; ++i) { const int idx = tid + 512 * i, t = idx >> 5, s0 = (idx & 31) * 4;
;             const f32x4 x = *(const f32x4*)(wsp + (size_t)(g * 128 + t) * 128 + s0);
;             u32x2 o; o.x = cvt2(s0 <= t ? x[0] : 0.f, s0 + 1 <= t ? x[1] : 0.f); o.y = cvt2(s0 + 2 <= t ? x[2] : 0.f, s0 + 3 <= t ? x[3] : 0.f);
;             *(LAS u32x2*)(wt + t * QK_STRIDE + s0 * 2) = o; }
;         __syncthreads();
;         f32x4 acc[8];
; #pragma unroll
;         for (int ct = 0; ct < 8; ++ct) acc[ct] = (f32x4){0.f, 0.f, 0.f, 0.f};
;         for (int ks = 0; ks <= (w >> 1); ++ks) { const bf16x8 bW = LDFRAG(wt, 16 * w + fr, QK_STRIDE, 32 * ks + 8 * fq);
; #pragma unroll
;             for (int ct = 0; ct < 8; ++ct) acc[ct] = MFMA16(LDFRAG(vnt, 16 * ct + fr, QK_STRIDE, 32 * ks + 8 * fq), bW, acc[ct]); }
;         const int t = 16 * w + fr; const float bt = bsp[g * 128 + t];
; #pragma unroll
;         for (int ct = 0; ct < 8; ++ct) { const int c0 = g * 128 + 16 * ct + 4 * fq; const u32x2 uu = *(const u32x2*)(U + (r0 + t) * AW + c0);
;             u32x2 o; o.x = cvt2(gelu_(bf2f(uu.x & 0xffff)) * (acc[ct][0] + bt), gelu_(bf2f(uu.x >> 16)) * (acc[ct][1] + bt));
;             o.y = cvt2(gelu_(bf2f(uu.y & 0xffff)) * (acc[ct][2] + bt), gelu_(bf2f(uu.y >> 16)) * (acc[ct][3] + bt));
;             *(u32x2*)(O + (r0 + t) * D + 512 + c0) = o; }
;         __syncthreads();
	v_lshlrev_b32_e32 v16, 16, v17
	v_and_b32_e32 v17, 0xffff0000, v17
	v_add_f32_e32 v0, 1.0, v0
	v_rcp_f32_e32 v21, v0
	v_mul_f32_e32 v0, 0x3d372713, v16
	v_mul_f32_e32 v0, v0, v16
	v_pk_mul_f32 v[18:19], v[20:21], v[18:19]
	s_nop 0
	v_pk_mul_f32 v[12:13], v[12:13], v[18:19]
	s_nop 0
	v_cvt_pk_bf16_f32 v12, v12, v13
	v_mov_b32_e32 v13, v16
	v_fmac_f32_e32 v13, v0, v13
	v_mul_f32_e32 v0, 0x3fcc422a, v13
	v_mul_f32_e32 v0, 0xbfb8aa3b, v0
	v_exp_f32_e32 v0, v0
	v_mov_b32_e32 v13, v17
	v_add_f32_e32 v0, 1.0, v0
	v_rcp_f32_e32 v18, v0
	v_mul_f32_e32 v0, 0x3d372713, v17
	v_mul_f32_e32 v0, v0, v17
	v_fmac_f32_e32 v13, v0, v13
	v_mul_f32_e32 v0, 0x3fcc422a, v13
	v_mul_f32_e32 v0, 0xbfb8aa3b, v0
	v_exp_f32_e32 v0, v0
	s_nop 0
	v_add_f32_e32 v0, 1.0, v0
	v_rcp_f32_e32 v19, v0
	s_nop 0
	v_pk_mul_f32 v[16:17], v[18:19], v[16:17]
	s_nop 0
	v_pk_mul_f32 v[14:15], v[14:15], v[16:17]
	s_nop 0
	v_cvt_pk_bf16_f32 v13, v14, v15
	global_store_dwordx2 v[36:37], v[12:13], off offset:1216
	v_mov_b32_e32 v12, v110
	v_mov_b32_e32 v13, v111
	v_lshlrev_b32_e32 v14, 16, v12
	v_mul_f32_e32 v0, 0x3d372713, v14
	v_and_b32_e32 v15, 0xffff0000, v12
	v_mul_f32_e32 v0, v0, v14
	v_mov_b32_e32 v12, v14
	v_fmac_f32_e32 v12, v0, v12
	v_mul_f32_e32 v0, 0x3fcc422a, v12
	v_mul_f32_e32 v0, 0xbfb8aa3b, v0
	v_exp_f32_e32 v0, v0
	v_mov_b32_e32 v12, v15
	v_add_f32_e32 v0, 1.0, v0
	v_rcp_f32_e32 v16, v0
	v_mul_f32_e32 v0, 0x3d372713, v15
	v_mul_f32_e32 v0, v0, v15
	v_fmac_f32_e32 v12, v0, v12
	v_mul_f32_e32 v0, 0x3fcc422a, v12
	v_mul_f32_e32 v0, 0xbfb8aa3b, v0
	v_exp_f32_e32 v0, v0
	v_lshlrev_b32_e32 v12, 16, v13
	v_and_b32_e32 v13, 0xffff0000, v13
	v_add_f32_e32 v0, 1.0, v0
	v_rcp_f32_e32 v17, v0
	v_mul_f32_e32 v0, 0x3d372713, v12
	v_mul_f32_e32 v0, v0, v12
	v_pk_mul_f32 v[14:15], v[16:17], v[14:15]
	s_nop 0
	v_pk_mul_f32 v[8:9], v[8:9], v[14:15]
	s_nop 0
	v_cvt_pk_bf16_f32 v8, v8, v9
	v_mov_b32_e32 v9, v12
	v_fmac_f32_e32 v9, v0, v9
	v_mul_f32_e32 v0, 0x3fcc422a, v9
	v_mul_f32_e32 v0, 0xbfb8aa3b, v0
	v_exp_f32_e32 v0, v0
	v_mov_b32_e32 v9, v13
	v_add_f32_e32 v0, 1.0, v0
	v_rcp_f32_e32 v14, v0
	v_mul_f32_e32 v0, 0x3d372713, v13
	v_mul_f32_e32 v0, v0, v13
	v_fmac_f32_e32 v9, v0, v9
	v_mul_f32_e32 v0, 0x3fcc422a, v9
	v_mul_f32_e32 v0, 0xbfb8aa3b, v0
	v_exp_f32_e32 v0, v0
	s_nop 0
	v_add_f32_e32 v0, 1.0, v0
	v_rcp_f32_e32 v15, v0
	s_nop 0
	v_pk_mul_f32 v[12:13], v[14:15], v[12:13]
	s_nop 0
	v_pk_mul_f32 v[10:11], v[10:11], v[12:13]
	s_nop 0
	v_cvt_pk_bf16_f32 v9, v10, v11
	global_store_dwordx2 v[36:37], v[8:9], off offset:1248
	s_barrier
	s_cbranch_scc1 .LBB0_144
.LBB0_151:
	s_lshl_b32 s36, s41, 7
	v_add_u32_e32 v144, s36, v70
	v_ashrrev_i32_e32 v145, 31, v144
	v_lshlrev_b64 v[144:145], 9, v[144:145]
	v_lshl_add_u64 v[144:145], v[54:55], 0, v[144:145]
	global_load_dwordx4 v[112:115], v[144:145], off
	v_add_u32_e32 v144, s36, v71
	v_ashrrev_i32_e32 v145, 31, v144
	v_lshlrev_b64 v[144:145], 9, v[144:145]
	v_lshl_add_u64 v[144:145], v[54:55], 0, v[144:145]
	global_load_dwordx4 v[116:119], v[144:145], off
	v_add_u32_e32 v144, s36, v72
	v_ashrrev_i32_e32 v145, 31, v144
	v_lshlrev_b64 v[144:145], 9, v[144:145]
	v_lshl_add_u64 v[144:145], v[54:55], 0, v[144:145]
	global_load_dwordx4 v[120:123], v[144:145], off
	v_add_u32_e32 v144, s36, v73
	v_ashrrev_i32_e32 v145, 31, v144
	v_lshlrev_b64 v[144:145], 9, v[144:145]
	v_lshl_add_u64 v[144:145], v[54:55], 0, v[144:145]
	global_load_dwordx4 v[124:127], v[144:145], off
	v_add_u32_e32 v144, s36, v74
	v_ashrrev_i32_e32 v145, 31, v144
	v_lshlrev_b64 v[144:145], 9, v[144:145]
	v_lshl_add_u64 v[144:145], v[54:55], 0, v[144:145]
	global_load_dwordx4 v[128:131], v[144:145], off
	v_add_u32_e32 v144, s36, v75
	v_ashrrev_i32_e32 v145, 31, v144
	v_lshlrev_b64 v[144:145], 9, v[144:145]
	v_lshl_add_u64 v[144:145], v[54:55], 0, v[144:145]
	global_load_dwordx4 v[132:135], v[144:145], off
	v_add_u32_e32 v144, s36, v76
	v_ashrrev_i32_e32 v145, 31, v144
	v_lshlrev_b64 v[144:145], 9, v[144:145]
	v_lshl_add_u64 v[144:145], v[54:55], 0, v[144:145]
	global_load_dwordx4 v[136:139], v[144:145], off
	v_add_u32_e32 v144, s36, v77
	v_ashrrev_i32_e32 v145, 31, v144
	v_lshlrev_b64 v[144:145], 9, v[144:145]
	v_lshl_add_u64 v[144:145], v[54:55], 0, v[144:145]
	global_load_dwordx4 v[140:143], v[144:145], off
	v_add_u32_e32 v144, s36, v56
	v_ashrrev_i32_e32 v145, 31, v144
	v_lshl_add_u64 v[144:145], v[144:145], 2, s[30:31]
	global_load_dword v148, v[144:145], off
	v_or_b32_e32 v146, s36, v69
	v_lshlrev_b32_e32 v146, 1, v146
	v_mov_b32_e32 v147, 0
	v_lshl_add_u64 v[144:145], v[58:59], 0, v[146:147]
	global_load_dwordx2 v[96:97], v[144:145], off
	global_load_dwordx2 v[98:99], v[144:145], off offset:32
	global_load_dwordx2 v[100:101], v[144:145], off offset:64
	global_load_dwordx2 v[102:103], v[144:145], off offset:96
	global_load_dwordx2 v[104:105], v[144:145], off offset:128
	global_load_dwordx2 v[106:107], v[144:145], off offset:160
	global_load_dwordx2 v[108:109], v[144:145], off offset:192
	global_load_dwordx2 v[110:111], v[144:145], off offset:224
	s_lshl_b32 s2, s41, 8
	s_mov_b32 s3, s37
	v_lshl_add_u64 v[28:29], v[52:53], 0, s[2:3]
	v_lshl_add_u64 v[8:9], v[40:41], 1, v[28:29]
	ds_read_b32 v0, v63
	ds_read_b32 v30, v68
	global_load_dwordx4 v[8:11], v[8:9], off
	s_lshl_b32 s36, s41, 7
	s_lshl_b64 s[16:17], s[36:37], 2
	s_add_u32 s2, s14, s16
	s_addc_u32 s3, s15, s17
	s_add_u32 vcc_lo, s35, s16
	s_addc_u32 vcc_hi, s23, s17
	v_lshlrev_b64 v[20:21], 2, v[40:41]
	v_lshl_add_u64 v[16:17], s[2:3], 0, v[20:21]
	v_lshl_add_u64 v[24:25], vcc, 0, v[20:21]
	global_load_dwordx4 v[12:15], v[16:17], off offset:16
	s_nop 0
	global_load_dwordx4 v[16:19], v[16:17], off
	s_nop 0
	global_load_dwordx4 v[20:23], v[24:25], off offset:16
	s_nop 0
	global_load_dwordx4 v[24:27], v[24:25], off
	s_waitcnt vmcnt(4)
; #define LAS __attribute__((address_space(3)))
; __device__ __forceinline__ float bf2f(unsigned h) { return __uint_as_float(h << 16); }
; __device__ __forceinline__ unsigned cvt2(float lo, float hi) { bf16v2_t r = __builtin_convertvector((f32x2){lo, hi}, bf16v2_t); return __builtin_bit_cast(unsigned, r); }
; __device__ __forceinline__ float gelu_(float x) { return x * sigm_(1.5957691216f * (x + 0.044715f * x * x * x)); }
; __device__ __forceinline__ void gmlp_mfma(LAS unsigned char* lds, const unsigned char* R, bf16_t* O, const float* lng, const float* lnb, const float* wsp, const float* bsp, int unit, int tid) {
;     ...
;         for (int i = 0; i < 4; ++i) { const int idx = tid + 512 * i, s = idx & 127, ch = idx >> 7;
;             const u32x4 x4 = *(const u32x4*)(VV + (r0 + s) * AW + g * 128 + ch * 8);
;             const f32x4 ga = *(const f32x4*)(lng + g * 128 + ch * 8), gb = *(const f32x4*)(lng + g * 128 + ch * 8 + 4), ba = *(const f32x4*)(lnb + g * 128 + ch * 8), bb = *(const f32x4*)(lnb + g * 128 + ch * 8 + 4);
;             const float m_ = mu[s], r_ = rs[s];
;             LAS unsigned short* d = (LAS unsigned short*)(vnt + (ch * 8) * QK_STRIDE + s * 2);
;             d[0 * (QK_STRIDE / 2)] = (unsigned short)(cvt2((gelu_(bf2f(x4.x & 0xffff)) - m_) * r_ * ga[0] + ba[0], 0.f) & 0xffff);
;             d[1 * (QK_STRIDE / 2)] = (unsigned short)(cvt2((gelu_(bf2f(x4.x >> 16)) - m_) * r_ * ga[1] + ba[1], 0.f) & 0xffff);
;             d[2 * (QK_STRIDE / 2)] = (unsigned short)(cvt2((gelu_(bf2f(x4.y & 0xffff)) - m_) * r_ * ga[2] + ba[2], 0.f) & 0xffff);
;             d[3 * (QK_STRIDE / 2)] = (unsigned short)(cvt2((gelu_(bf2f(x4.y >> 16)) - m_) * r_ * ga[3] + ba[3], 0.f) & 0xffff);
;             d[4 * (QK_STRIDE / 2)] = (unsigned short)(cvt2((gelu_(bf2f(x4.z & 0xffff)) - m_) * r_ * gb[0] + bb[0], 0.f) & 0xffff);
;             d[5 * (QK_STRIDE / 2)] = (unsigned short)(cvt2((gelu_(bf2f(x4.z >> 16)) - m_) * r_ * gb[1] + bb[1], 0.f) & 0xffff);
;             d[6 * (QK_STRIDE / 2)] = (unsigned short)(cvt2((gelu_(bf2f(x4.w & 0xffff)) - m_) * r_ * gb[2] + bb[2], 0.f) & 0xffff);
;             d[7 * (QK_STRIDE / 2)] = (unsigned short)(cvt2((gelu_(bf2f(x4.w >> 16)) - m_) * r_ * gb[3] + bb[3], 0.f) & 0xffff); }
	v_lshlrev_b32_e32 v31, 16, v8
	v_mul_f32_e32 v32, 0x3d372713, v31
	v_mul_f32_e32 v32, v32, v31
	v_fma_f32 v32, v32, v31, v31
	v_mul_f32_e32 v32, 0x3fcc422a, v32
	v_mul_f32_e32 v32, 0xbfb8aa3b, v32
	v_exp_f32_e32 v32, v32
	v_and_b32_e32 v8, 0xffff0000, v8
	v_add_f32_e32 v32, 1.0, v32
	v_rcp_f32_e32 v32, v32
	s_waitcnt lgkmcnt(1)
	v_fma_f32 v31, v32, v31, -v0
	s_waitcnt lgkmcnt(0)
	v_mul_f32_e32 v31, v30, v31
	s_waitcnt vmcnt(0)
	v_fma_f32 v16, v16, v31, v24
	v_cvt_pk_bf16_f32 v16, v16, s0
	ds_write_b16 v80, v16
	v_mul_f32_e32 v16, 0x3d372713, v8
	v_mul_f32_e32 v16, v16, v8
	v_fma_f32 v16, v16, v8, v8
	v_mul_f32_e32 v16, 0x3fcc422a, v16
	v_mul_f32_e32 v16, 0xbfb8aa3b, v16
	v_exp_f32_e32 v16, v16
	s_nop 0
	v_add_f32_e32 v16, 1.0, v16
	v_rcp_f32_e32 v16, v16
	s_nop 0
	v_fma_f32 v8, v16, v8, -v0
	v_mul_f32_e32 v8, v30, v8
	v_fma_f32 v8, v17, v8, v25
	v_cvt_pk_bf16_f32 v8, v8, s0
	ds_write_b16 v80, v8 offset:272
	v_lshlrev_b32_e32 v8, 16, v9
	v_mul_f32_e32 v16, 0x3d372713, v8
	v_mul_f32_e32 v16, v16, v8
	v_fma_f32 v16, v16, v8, v8
	v_mul_f32_e32 v16, 0x3fcc422a, v16
	v_mul_f32_e32 v16, 0xbfb8aa3b, v16
	v_exp_f32_e32 v16, v16
	s_nop 0
	v_add_f32_e32 v16, 1.0, v16
	v_rcp_f32_e32 v16, v16
	s_nop 0
	v_fma_f32 v8, v16, v8, -v0
	v_mul_f32_e32 v8, v30, v8
	v_fma_f32 v8, v18, v8, v26
	v_cvt_pk_bf16_f32 v8, v8, s0
	ds_write_b16 v80, v8 offset:544
	v_and_b32_e32 v8, 0xffff0000, v9
	v_mul_f32_e32 v9, 0x3d372713, v8
	v_mul_f32_e32 v9, v9, v8
	v_fma_f32 v9, v9, v8, v8
	v_mul_f32_e32 v9, 0x3fcc422a, v9
	v_mul_f32_e32 v9, 0xbfb8aa3b, v9
	v_exp_f32_e32 v9, v9
	v_lshlrev_b64 v[16:17], 2, v[42:43]
	v_lshl_add_u64 v[24:25], vcc, 0, v[16:17]
	v_add_f32_e32 v9, 1.0, v9
	v_rcp_f32_e32 v9, v9
	s_nop 0
	v_fma_f32 v8, v9, v8, -v0
	v_mul_f32_e32 v8, v30, v8
	v_fmac_f32_e32 v27, v19, v8
	v_cvt_pk_bf16_f32 v8, v27, s0
	ds_write_b16 v80, v8 offset:816
	v_lshlrev_b32_e32 v8, 16, v10
	v_mul_f32_e32 v9, 0x3d372713, v8
	v_mul_f32_e32 v9, v9, v8
	v_fma_f32 v9, v9, v8, v8
	v_mul_f32_e32 v9, 0x3fcc422a, v9
	v_mul_f32_e32 v9, 0xbfb8aa3b, v9
	v_exp_f32_e32 v9, v9
	v_lshl_add_u64 v[18:19], s[2:3], 0, v[16:17]
	v_add_f32_e32 v9, 1.0, v9
	v_rcp_f32_e32 v9, v9
	s_nop 0
	v_fma_f32 v8, v9, v8, -v0
	v_mul_f32_e32 v8, v30, v8
	v_fma_f32 v8, v12, v8, v20
	v_cvt_pk_bf16_f32 v8, v8, s0
	ds_write_b16 v80, v8 offset:1088
	v_and_b32_e32 v8, 0xffff0000, v10
	v_mul_f32_e32 v9, 0x3d372713, v8
	v_mul_f32_e32 v9, v9, v8
	v_fma_f32 v9, v9, v8, v8
	v_mul_f32_e32 v9, 0x3fcc422a, v9
	v_mul_f32_e32 v9, 0xbfb8aa3b, v9
	v_exp_f32_e32 v9, v9
	s_nop 0
	v_add_f32_e32 v9, 1.0, v9
	v_rcp_f32_e32 v9, v9
	s_nop 0
	v_fma_f32 v8, v9, v8, -v0
	v_mul_f32_e32 v8, v30, v8
	v_fma_f32 v8, v13, v8, v21
	v_cvt_pk_bf16_f32 v8, v8, s0
	ds_write_b16 v80, v8 offset:1360
	v_lshlrev_b32_e32 v8, 16, v11
	v_mul_f32_e32 v9, 0x3d372713, v8
	v_mul_f32_e32 v9, v9, v8
	v_fma_f32 v9, v9, v8, v8
	v_mul_f32_e32 v9, 0x3fcc422a, v9
	v_mul_f32_e32 v9, 0xbfb8aa3b, v9
	v_exp_f32_e32 v9, v9
	s_nop 0
	v_add_f32_e32 v9, 1.0, v9
	v_rcp_f32_e32 v9, v9
	s_nop 0
	v_fma_f32 v8, v9, v8, -v0
	v_mul_f32_e32 v8, v30, v8
	v_fma_f32 v8, v14, v8, v22
	v_cvt_pk_bf16_f32 v8, v8, s0
	ds_write_b16 v80, v8 offset:1632
	v_and_b32_e32 v8, 0xffff0000, v11
	v_mul_f32_e32 v9, 0x3d372713, v8
	v_mul_f32_e32 v9, v9, v8
	v_fma_f32 v9, v9, v8, v8
	v_mul_f32_e32 v9, 0x3fcc422a, v9
	v_mul_f32_e32 v9, 0xbfb8aa3b, v9
	v_exp_f32_e32 v9, v9
	s_nop 0
	v_add_f32_e32 v9, 1.0, v9
	v_rcp_f32_e32 v9, v9
	s_nop 0
	v_fma_f32 v8, v9, v8, -v0
	v_mul_f32_e32 v8, v30, v8
	v_fmac_f32_e32 v23, v15, v8
	v_cvt_pk_bf16_f32 v8, v23, s0
	ds_write_b16 v80, v8 offset:1904
	v_lshl_add_u64 v[8:9], v[42:43], 1, v[28:29]
	global_load_dwordx4 v[8:11], v[8:9], off
	s_nop 0
	global_load_dwordx4 v[12:15], v[18:19], off offset:16
	global_load_dwordx4 v[20:23], v[18:19], off
	s_nop 0
	global_load_dwordx4 v[16:19], v[24:25], off offset:16
	s_nop 0
	global_load_dwordx4 v[24:27], v[24:25], off
	s_waitcnt vmcnt(4)
	v_lshlrev_b32_e32 v31, 16, v8
	v_mul_f32_e32 v32, 0x3d372713, v31
	v_mul_f32_e32 v32, v32, v31
	v_fma_f32 v32, v32, v31, v31
	v_mul_f32_e32 v32, 0x3fcc422a, v32
	v_mul_f32_e32 v32, 0xbfb8aa3b, v32
	v_exp_f32_e32 v32, v32
	v_and_b32_e32 v8, 0xffff0000, v8
	v_add_f32_e32 v32, 1.0, v32
	v_rcp_f32_e32 v32, v32
	s_nop 0
	v_fma_f32 v31, v32, v31, -v0
	v_mul_f32_e32 v31, v30, v31
	s_waitcnt vmcnt(0)
; #define LAS __attribute__((address_space(3)))
; __device__ __forceinline__ float bf2f(unsigned h) { return __uint_as_float(h << 16); }
; __device__ __forceinline__ unsigned cvt2(float lo, float hi) { bf16v2_t r = __builtin_convertvector((f32x2){lo, hi}, bf16v2_t); return __builtin_bit_cast(unsigned, r); }
; __device__ __forceinline__ float gelu_(float x) { return x * sigm_(1.5957691216f * (x + 0.044715f * x * x * x)); }
; __device__ __forceinline__ void gmlp_mfma(LAS unsigned char* lds, const unsigned char* R, bf16_t* O, const float* lng, const float* lnb, const float* wsp, const float* bsp, int unit, int tid) {
;     ...
;         for (int i = 0; i < 4; ++i) { const int idx = tid + 512 * i, s = idx & 127, ch = idx >> 7;
;             const u32x4 x4 = *(const u32x4*)(VV + (r0 + s) * AW + g * 128 + ch * 8);
;             const f32x4 ga = *(const f32x4*)(lng + g * 128 + ch * 8), gb = *(const f32x4*)(lng + g * 128 + ch * 8 + 4), ba = *(const f32x4*)(lnb + g * 128 + ch * 8), bb = *(const f32x4*)(lnb + g * 128 + ch * 8 + 4);
;             const float m_ = mu[s], r_ = rs[s];
;             LAS unsigned short* d = (LAS unsigned short*)(vnt + (ch * 8) * QK_STRIDE + s * 2);
;             d[0 * (QK_STRIDE / 2)] = (unsigned short)(cvt2((gelu_(bf2f(x4.x & 0xffff)) - m_) * r_ * ga[0] + ba[0], 0.f) & 0xffff);
;             d[1 * (QK_STRIDE / 2)] = (unsigned short)(cvt2((gelu_(bf2f(x4.x >> 16)) - m_) * r_ * ga[1] + ba[1], 0.f) & 0xffff);
;             d[2 * (QK_STRIDE / 2)] = (unsigned short)(cvt2((gelu_(bf2f(x4.y & 0xffff)) - m_) * r_ * ga[2] + ba[2], 0.f) & 0xffff);
;             d[3 * (QK_STRIDE / 2)] = (unsigned short)(cvt2((gelu_(bf2f(x4.y >> 16)) - m_) * r_ * ga[3] + ba[3], 0.f) & 0xffff);
;             d[4 * (QK_STRIDE / 2)] = (unsigned short)(cvt2((gelu_(bf2f(x4.z & 0xffff)) - m_) * r_ * gb[0] + bb[0], 0.f) & 0xffff);
;             d[5 * (QK_STRIDE / 2)] = (unsigned short)(cvt2((gelu_(bf2f(x4.z >> 16)) - m_) * r_ * gb[1] + bb[1], 0.f) & 0xffff);
;             d[6 * (QK_STRIDE / 2)] = (unsigned short)(cvt2((gelu_(bf2f(x4.w & 0xffff)) - m_) * r_ * gb[2] + bb[2], 0.f) & 0xffff);
;             d[7 * (QK_STRIDE / 2)] = (unsigned short)(cvt2((gelu_(bf2f(x4.w >> 16)) - m_) * r_ * gb[3] + bb[3], 0.f) & 0xffff); }
	v_fma_f32 v20, v20, v31, v24
	v_cvt_pk_bf16_f32 v20, v20, s0
	ds_write_b16 v81, v20
	v_mul_f32_e32 v20, 0x3d372713, v8
	v_mul_f32_e32 v20, v20, v8
	v_fma_f32 v20, v20, v8, v8
	v_mul_f32_e32 v20, 0x3fcc422a, v20
	v_mul_f32_e32 v20, 0xbfb8aa3b, v20
	v_exp_f32_e32 v20, v20
	s_nop 0
	v_add_f32_e32 v20, 1.0, v20
	v_rcp_f32_e32 v20, v20
	s_nop 0
	v_fma_f32 v8, v20, v8, -v0
	v_mul_f32_e32 v8, v30, v8
	v_fma_f32 v8, v21, v8, v25
	v_cvt_pk_bf16_f32 v8, v8, s0
	ds_write_b16 v81, v8 offset:272
	v_lshlrev_b32_e32 v8, 16, v9
	v_mul_f32_e32 v20, 0x3d372713, v8
	v_mul_f32_e32 v20, v20, v8
	v_fma_f32 v20, v20, v8, v8
	v_mul_f32_e32 v20, 0x3fcc422a, v20
	v_mul_f32_e32 v20, 0xbfb8aa3b, v20
	v_exp_f32_e32 v20, v20
	s_nop 0
	v_add_f32_e32 v20, 1.0, v20
	v_rcp_f32_e32 v20, v20
	s_nop 0
	v_fma_f32 v8, v20, v8, -v0
	v_mul_f32_e32 v8, v30, v8
	v_fma_f32 v8, v22, v8, v26
	v_cvt_pk_bf16_f32 v8, v8, s0
	ds_write_b16 v81, v8 offset:544
	v_and_b32_e32 v8, 0xffff0000, v9
	v_mul_f32_e32 v9, 0x3d372713, v8
	v_mul_f32_e32 v9, v9, v8
	v_fma_f32 v9, v9, v8, v8
	v_mul_f32_e32 v9, 0x3fcc422a, v9
	v_mul_f32_e32 v9, 0xbfb8aa3b, v9
	v_exp_f32_e32 v9, v9
	s_nop 0
	v_add_f32_e32 v9, 1.0, v9
	v_rcp_f32_e32 v9, v9
	s_nop 0
	v_fma_f32 v8, v9, v8, -v0
	v_mul_f32_e32 v8, v30, v8
	v_fmac_f32_e32 v27, v23, v8
	v_cvt_pk_bf16_f32 v8, v27, s0
	ds_write_b16 v81, v8 offset:816
	v_lshlrev_b32_e32 v8, 16, v10
	v_mul_f32_e32 v9, 0x3d372713, v8
	v_mul_f32_e32 v9, v9, v8
	v_fma_f32 v9, v9, v8, v8
	v_mul_f32_e32 v9, 0x3fcc422a, v9
	v_mul_f32_e32 v9, 0xbfb8aa3b, v9
	v_exp_f32_e32 v9, v9
	s_nop 0
	v_add_f32_e32 v9, 1.0, v9
	v_rcp_f32_e32 v9, v9
	s_nop 0
	v_fma_f32 v8, v9, v8, -v0
	v_mul_f32_e32 v8, v30, v8
	v_fma_f32 v8, v12, v8, v16
	v_cvt_pk_bf16_f32 v8, v8, s0
	ds_write_b16 v81, v8 offset:1088
	v_and_b32_e32 v8, 0xffff0000, v10
	v_mul_f32_e32 v9, 0x3d372713, v8
	v_mul_f32_e32 v9, v9, v8
	v_fma_f32 v9, v9, v8, v8
	v_mul_f32_e32 v9, 0x3fcc422a, v9
	v_mul_f32_e32 v9, 0xbfb8aa3b, v9
	v_exp_f32_e32 v9, v9
	s_nop 0
	v_add_f32_e32 v9, 1.0, v9
	v_rcp_f32_e32 v9, v9
	s_nop 0
	v_fma_f32 v8, v9, v8, -v0
	v_mul_f32_e32 v8, v30, v8
	v_fma_f32 v8, v13, v8, v17
	v_cvt_pk_bf16_f32 v8, v8, s0
	ds_write_b16 v81, v8 offset:1360
	v_lshlrev_b32_e32 v8, 16, v11
	v_mul_f32_e32 v9, 0x3d372713, v8
	v_mul_f32_e32 v9, v9, v8
	v_fma_f32 v9, v9, v8, v8
	v_mul_f32_e32 v9, 0x3fcc422a, v9
	v_mul_f32_e32 v9, 0xbfb8aa3b, v9
	v_exp_f32_e32 v9, v9
	v_lshlrev_b64 v[16:17], 2, v[44:45]
	v_lshl_add_u64 v[24:25], vcc, 0, v[16:17]
	v_add_f32_e32 v9, 1.0, v9
	v_rcp_f32_e32 v9, v9
	s_nop 0
	v_fma_f32 v8, v9, v8, -v0
	v_mul_f32_e32 v8, v30, v8
	v_fma_f32 v8, v14, v8, v18
	v_cvt_pk_bf16_f32 v8, v8, s0
	ds_write_b16 v81, v8 offset:1632
	v_and_b32_e32 v8, 0xffff0000, v11
	v_mul_f32_e32 v9, 0x3d372713, v8
	v_mul_f32_e32 v9, v9, v8
	v_fma_f32 v9, v9, v8, v8
	v_mul_f32_e32 v9, 0x3fcc422a, v9
	v_mul_f32_e32 v9, 0xbfb8aa3b, v9
	v_exp_f32_e32 v9, v9
	s_nop 0
	v_add_f32_e32 v9, 1.0, v9
	v_rcp_f32_e32 v9, v9
	s_nop 0
	v_fma_f32 v8, v9, v8, -v0
	v_mul_f32_e32 v8, v30, v8
	v_fmac_f32_e32 v19, v15, v8
	v_cvt_pk_bf16_f32 v8, v19, s0
	ds_write_b16 v81, v8 offset:1904
	v_lshl_add_u64 v[8:9], v[44:45], 1, v[28:29]
	global_load_dwordx4 v[8:11], v[8:9], off
	v_lshl_add_u64 v[18:19], s[2:3], 0, v[16:17]
	global_load_dwordx4 v[12:15], v[18:19], off offset:16
	global_load_dwordx4 v[20:23], v[18:19], off
	s_nop 0
	global_load_dwordx4 v[16:19], v[24:25], off offset:16
	s_nop 0
	global_load_dwordx4 v[24:27], v[24:25], off
	s_waitcnt vmcnt(4)
	v_lshlrev_b32_e32 v31, 16, v8
	v_mul_f32_e32 v32, 0x3d372713, v31
	v_mul_f32_e32 v32, v32, v31
	v_fma_f32 v32, v32, v31, v31
	v_mul_f32_e32 v32, 0x3fcc422a, v32
	v_mul_f32_e32 v32, 0xbfb8aa3b, v32
	v_exp_f32_e32 v32, v32
	v_and_b32_e32 v8, 0xffff0000, v8
	v_add_f32_e32 v32, 1.0, v32
	v_rcp_f32_e32 v32, v32
	s_nop 0
	v_fma_f32 v31, v32, v31, -v0
	v_mul_f32_e32 v31, v30, v31
	s_waitcnt vmcnt(0)
	v_fma_f32 v20, v20, v31, v24
	v_cvt_pk_bf16_f32 v20, v20, s0
	ds_write_b16 v82, v20
	v_mul_f32_e32 v20, 0x3d372713, v8
	v_mul_f32_e32 v20, v20, v8
	v_fma_f32 v20, v20, v8, v8
	v_mul_f32_e32 v20, 0x3fcc422a, v20
	v_mul_f32_e32 v20, 0xbfb8aa3b, v20
	v_exp_f32_e32 v20, v20
	s_nop 0
	v_add_f32_e32 v20, 1.0, v20
	v_rcp_f32_e32 v20, v20
	s_nop 0
	v_fma_f32 v8, v20, v8, -v0
	v_mul_f32_e32 v8, v30, v8
	v_fma_f32 v8, v21, v8, v25
	v_cvt_pk_bf16_f32 v8, v8, s0
	ds_write_b16 v82, v8 offset:272
	v_lshlrev_b32_e32 v8, 16, v9
	v_mul_f32_e32 v20, 0x3d372713, v8
	v_mul_f32_e32 v20, v20, v8
	v_fma_f32 v20, v20, v8, v8
	v_mul_f32_e32 v20, 0x3fcc422a, v20
	v_mul_f32_e32 v20, 0xbfb8aa3b, v20
	v_exp_f32_e32 v20, v20
	s_nop 0
	v_add_f32_e32 v20, 1.0, v20
	v_rcp_f32_e32 v20, v20
	s_nop 0
	v_fma_f32 v8, v20, v8, -v0
	v_mul_f32_e32 v8, v30, v8
	v_fma_f32 v8, v22, v8, v26
	v_cvt_pk_bf16_f32 v8, v8, s0
	ds_write_b16 v82, v8 offset:544
	v_and_b32_e32 v8, 0xffff0000, v9
	v_mul_f32_e32 v9, 0x3d372713, v8
	v_mul_f32_e32 v9, v9, v8
	v_fma_f32 v9, v9, v8, v8
	v_mul_f32_e32 v9, 0x3fcc422a, v9
	v_mul_f32_e32 v9, 0xbfb8aa3b, v9
	v_exp_f32_e32 v9, v9
	s_nop 0
	v_add_f32_e32 v9, 1.0, v9
	v_rcp_f32_e32 v9, v9
	s_nop 0
	v_fma_f32 v8, v9, v8, -v0
	v_mul_f32_e32 v8, v30, v8
	v_fmac_f32_e32 v27, v23, v8
	v_cvt_pk_bf16_f32 v8, v27, s0
	ds_write_b16 v82, v8 offset:816
	v_lshlrev_b32_e32 v8, 16, v10
	v_mul_f32_e32 v9, 0x3d372713, v8
	v_mul_f32_e32 v9, v9, v8
	v_fma_f32 v9, v9, v8, v8
	v_mul_f32_e32 v9, 0x3fcc422a, v9
	v_mul_f32_e32 v9, 0xbfb8aa3b, v9
	v_exp_f32_e32 v9, v9
	s_nop 0
	v_add_f32_e32 v9, 1.0, v9
	v_rcp_f32_e32 v9, v9
	s_nop 0
	v_fma_f32 v8, v9, v8, -v0
	v_mul_f32_e32 v8, v30, v8
	v_fma_f32 v8, v12, v8, v16
	v_cvt_pk_bf16_f32 v8, v8, s0
	ds_write_b16 v82, v8 offset:1088
; #define LAS __attribute__((address_space(3)))
; __device__ __forceinline__ float bf2f(unsigned h) { return __uint_as_float(h << 16); }
; __device__ __forceinline__ void gmlp_mfma(LAS unsigned char* lds, const unsigned char* R, bf16_t* O, const float* lng, const float* lnb, const float* wsp, const float* bsp, int unit, int tid) {
;     ...
;         for (int i = 0; i < 4; ++i) { const int idx = tid + 512 * i, s = idx & 127, ch = idx >> 7;
;             const u32x4 x4 = *(const u32x4*)(VV + (r0 + s) * AW + g * 128 + ch * 8);
;             const f32x4 ga = *(const f32x4*)(lng + g * 128 + ch * 8), gb = *(const f32x4*)(lng + g * 128 + ch * 8 + 4), ba = *(const f32x4*)(lnb + g * 128 + ch * 8), bb = *(const f32x4*)(lnb + g * 128 + ch * 8 + 4);
;             const float m_ = mu[s], r_ = rs[s];
;             LAS unsigned short* d = (LAS unsigned short*)(vnt + (ch * 8) * QK_STRIDE + s * 2);
;             d[0 * (QK_STRIDE / 2)] = (unsigned short)(cvt2((gelu_(bf2f(x4.x & 0xffff)) - m_) * r_ * ga[0] + ba[0], 0.f) & 0xffff);
;             d[1 * (QK_STRIDE / 2)] = (unsigned short)(cvt2((gelu_(bf2f(x4.x >> 16)) - m_) * r_ * ga[1] + ba[1], 0.f) & 0xffff);
;             d[2 * (QK_STRIDE / 2)] = (unsigned short)(cvt2((gelu_(bf2f(x4.y & 0xffff)) - m_) * r_ * ga[2] + ba[2], 0.f) & 0xffff);
;             d[3 * (QK_STRIDE / 2)] = (unsigned short)(cvt2((gelu_(bf2f(x4.y >> 16)) - m_) * r_ * ga[3] + ba[3], 0.f) & 0xffff);
;             d[4 * (QK_STRIDE / 2)] = (unsigned short)(cvt2((gelu_(bf2f(x4.z & 0xffff)) - m_) * r_ * gb[0] + bb[0], 0.f) & 0xffff);
;             d[5 * (QK_STRIDE / 2)] = (unsigned short)(cvt2((gelu_(bf2f(x4.z >> 16)) - m_) * r_ * gb[1] + bb[1], 0.f) & 0xffff);
;             d[6 * (QK_STRIDE / 2)] = (unsigned short)(cvt2((gelu_(bf2f(x4.w & 0xffff)) - m_) * r_ * gb[2] + bb[2], 0.f) & 0xffff);
;             d[7 * (QK_STRIDE / 2)] = (unsigned short)(cvt2((gelu_(bf2f(x4.w >> 16)) - m_) * r_ * gb[3] + bb[3], 0.f) & 0xffff); }
; #pragma unroll
;         for (int i = 0; i < 8; ++i) { const int idx = tid + 512 * i, t = idx >> 5, s0 = (idx & 31) * 4;
;             const f32x4 x = *(const f32x4*)(wsp + (size_t)(g * 128 + t) * 128 + s0);
;             u32x2 o; o.x = cvt2(s0 <= t ? x[0] : 0.f, s0 + 1 <= t ? x[1] : 0.f); o.y = cvt2(s0 + 2 <= t ? x[2] : 0.f, s0 + 3 <= t ? x[3] : 0.f);
;             *(LAS u32x2*)(wt + t * QK_STRIDE + s0 * 2) = o; }
	v_and_b32_e32 v8, 0xffff0000, v10
	v_mul_f32_e32 v9, 0x3d372713, v8
	v_mul_f32_e32 v9, v9, v8
	v_fma_f32 v9, v9, v8, v8
	v_mul_f32_e32 v9, 0x3fcc422a, v9
	v_mul_f32_e32 v9, 0xbfb8aa3b, v9
	v_exp_f32_e32 v9, v9
	s_nop 0
	v_add_f32_e32 v9, 1.0, v9
	v_rcp_f32_e32 v9, v9
	s_nop 0
	v_fma_f32 v8, v9, v8, -v0
	v_mul_f32_e32 v8, v30, v8
	v_fma_f32 v8, v13, v8, v17
	v_cvt_pk_bf16_f32 v8, v8, s0
	ds_write_b16 v82, v8 offset:1360
	v_lshlrev_b32_e32 v8, 16, v11
	v_mul_f32_e32 v9, 0x3d372713, v8
	v_mul_f32_e32 v9, v9, v8
	v_fma_f32 v9, v9, v8, v8
	v_mul_f32_e32 v9, 0x3fcc422a, v9
	v_mul_f32_e32 v9, 0xbfb8aa3b, v9
	v_exp_f32_e32 v9, v9
	v_lshlrev_b64 v[16:17], 2, v[46:47]
	v_lshl_add_u64 v[24:25], vcc, 0, v[16:17]
	s_andn2_b64 vcc, exec, s[28:29]
	v_add_f32_e32 v9, 1.0, v9
	v_rcp_f32_e32 v9, v9
	s_nop 0
	v_fma_f32 v8, v9, v8, -v0
	v_mul_f32_e32 v8, v30, v8
	v_fma_f32 v8, v14, v8, v18
	v_cvt_pk_bf16_f32 v8, v8, s0
	ds_write_b16 v82, v8 offset:1632
	v_and_b32_e32 v8, 0xffff0000, v11
	v_mul_f32_e32 v9, 0x3d372713, v8
	v_mul_f32_e32 v9, v9, v8
	v_fma_f32 v9, v9, v8, v8
	v_mul_f32_e32 v9, 0x3fcc422a, v9
	v_mul_f32_e32 v9, 0xbfb8aa3b, v9
	v_exp_f32_e32 v9, v9
	s_nop 0
	v_add_f32_e32 v9, 1.0, v9
	v_rcp_f32_e32 v9, v9
	s_nop 0
	v_fma_f32 v8, v9, v8, -v0
	v_mul_f32_e32 v8, v30, v8
	v_fmac_f32_e32 v19, v15, v8
	v_cvt_pk_bf16_f32 v8, v19, s0
	ds_write_b16 v82, v8 offset:1904
	v_lshl_add_u64 v[8:9], v[46:47], 1, v[28:29]
	global_load_dwordx4 v[8:11], v[8:9], off
	v_lshl_add_u64 v[18:19], s[2:3], 0, v[16:17]
	global_load_dwordx4 v[12:15], v[18:19], off offset:16
	global_load_dwordx4 v[20:23], v[18:19], off
	s_nop 0
	global_load_dwordx4 v[16:19], v[24:25], off offset:16
	s_nop 0
	global_load_dwordx4 v[24:27], v[24:25], off
	s_waitcnt vmcnt(4)
	v_lshlrev_b32_e32 v28, 16, v8
	v_mul_f32_e32 v29, 0x3d372713, v28
	v_mul_f32_e32 v29, v29, v28
	v_fma_f32 v29, v29, v28, v28
	v_mul_f32_e32 v29, 0x3fcc422a, v29
	v_mul_f32_e32 v29, 0xbfb8aa3b, v29
	v_exp_f32_e32 v29, v29
	v_and_b32_e32 v8, 0xffff0000, v8
	v_add_f32_e32 v29, 1.0, v29
	v_rcp_f32_e32 v29, v29
	s_nop 0
	v_fma_f32 v28, v29, v28, -v0
	v_mul_f32_e32 v28, v30, v28
	s_waitcnt vmcnt(0)
	v_fma_f32 v20, v20, v28, v24
	v_cvt_pk_bf16_f32 v20, v20, s0
	ds_write_b16 v83, v20
	v_mul_f32_e32 v20, 0x3d372713, v8
	v_mul_f32_e32 v20, v20, v8
	v_fma_f32 v20, v20, v8, v8
	v_mul_f32_e32 v20, 0x3fcc422a, v20
	v_mul_f32_e32 v20, 0xbfb8aa3b, v20
	v_exp_f32_e32 v20, v20
	s_nop 0
	v_add_f32_e32 v20, 1.0, v20
	v_rcp_f32_e32 v20, v20
	s_nop 0
	v_fma_f32 v8, v20, v8, -v0
	v_mul_f32_e32 v8, v30, v8
	v_fma_f32 v8, v21, v8, v25
	v_cvt_pk_bf16_f32 v8, v8, s0
	ds_write_b16 v83, v8 offset:272
	v_lshlrev_b32_e32 v8, 16, v9
	v_mul_f32_e32 v20, 0x3d372713, v8
	v_mul_f32_e32 v20, v20, v8
	v_fma_f32 v20, v20, v8, v8
	v_mul_f32_e32 v20, 0x3fcc422a, v20
	v_mul_f32_e32 v20, 0xbfb8aa3b, v20
	v_exp_f32_e32 v20, v20
	s_nop 0
	v_add_f32_e32 v20, 1.0, v20
	v_rcp_f32_e32 v20, v20
	s_nop 0
	v_fma_f32 v8, v20, v8, -v0
	v_mul_f32_e32 v8, v30, v8
	v_fma_f32 v8, v22, v8, v26
	v_cvt_pk_bf16_f32 v8, v8, s0
	ds_write_b16 v83, v8 offset:544
	v_and_b32_e32 v8, 0xffff0000, v9
	v_mul_f32_e32 v9, 0x3d372713, v8
	v_mul_f32_e32 v9, v9, v8
	v_fma_f32 v9, v9, v8, v8
	v_mul_f32_e32 v9, 0x3fcc422a, v9
	v_mul_f32_e32 v9, 0xbfb8aa3b, v9
	v_exp_f32_e32 v9, v9
	s_nop 0
	v_add_f32_e32 v9, 1.0, v9
	v_rcp_f32_e32 v9, v9
	s_nop 0
	v_fma_f32 v8, v9, v8, -v0
	v_mul_f32_e32 v8, v30, v8
	v_fmac_f32_e32 v27, v23, v8
	v_cvt_pk_bf16_f32 v8, v27, s0
	ds_write_b16 v83, v8 offset:816
	v_lshlrev_b32_e32 v8, 16, v10
	v_mul_f32_e32 v9, 0x3d372713, v8
	v_mul_f32_e32 v9, v9, v8
	v_fma_f32 v9, v9, v8, v8
	v_mul_f32_e32 v9, 0x3fcc422a, v9
	v_mul_f32_e32 v9, 0xbfb8aa3b, v9
	v_exp_f32_e32 v9, v9
	s_nop 0
	v_add_f32_e32 v9, 1.0, v9
	v_rcp_f32_e32 v9, v9
	s_nop 0
	v_fma_f32 v8, v9, v8, -v0
	v_mul_f32_e32 v8, v30, v8
	v_fma_f32 v8, v12, v8, v16
	v_cvt_pk_bf16_f32 v8, v8, s0
	ds_write_b16 v83, v8 offset:1088
	v_and_b32_e32 v8, 0xffff0000, v10
	v_mul_f32_e32 v9, 0x3d372713, v8
	v_mul_f32_e32 v9, v9, v8
	v_fma_f32 v9, v9, v8, v8
	v_mul_f32_e32 v9, 0x3fcc422a, v9
	v_mul_f32_e32 v9, 0xbfb8aa3b, v9
	v_exp_f32_e32 v9, v9
	s_nop 0
	v_add_f32_e32 v9, 1.0, v9
	v_rcp_f32_e32 v9, v9
	s_nop 0
	v_fma_f32 v8, v9, v8, -v0
	v_mul_f32_e32 v8, v30, v8
	v_fma_f32 v8, v13, v8, v17
	v_cvt_pk_bf16_f32 v8, v8, s0
	ds_write_b16 v83, v8 offset:1360
	v_lshlrev_b32_e32 v8, 16, v11
	v_mul_f32_e32 v9, 0x3d372713, v8
	v_mul_f32_e32 v9, v9, v8
	v_fma_f32 v9, v9, v8, v8
	v_mul_f32_e32 v9, 0x3fcc422a, v9
	v_mul_f32_e32 v9, 0xbfb8aa3b, v9
	v_exp_f32_e32 v9, v9
	s_nop 0
	v_add_f32_e32 v9, 1.0, v9
	v_rcp_f32_e32 v9, v9
	s_nop 0
	v_fma_f32 v8, v9, v8, -v0
	v_mul_f32_e32 v8, v30, v8
	v_fma_f32 v8, v14, v8, v18
	v_cvt_pk_bf16_f32 v8, v8, s0
	ds_write_b16 v83, v8 offset:1632
	v_and_b32_e32 v8, 0xffff0000, v11
	v_mul_f32_e32 v9, 0x3d372713, v8
	v_mul_f32_e32 v9, v9, v8
	v_fma_f32 v9, v9, v8, v8
	v_mul_f32_e32 v9, 0x3fcc422a, v9
	v_mul_f32_e32 v9, 0xbfb8aa3b, v9
	v_exp_f32_e32 v9, v9
	s_nop 0
	v_add_f32_e32 v9, 1.0, v9
	v_rcp_f32_e32 v9, v9
	s_nop 0
	v_fma_f32 v0, v9, v8, -v0
	v_add_u32_e32 v8, s36, v70
	v_ashrrev_i32_e32 v9, 31, v8
	v_lshlrev_b64 v[8:9], 9, v[8:9]
	v_lshl_add_u64 v[8:9], v[54:55], 0, v[8:9]
	v_mov_b32_e32 v8, v112
	v_mov_b32_e32 v9, v113
	v_mov_b32_e32 v10, v114
	v_mov_b32_e32 v11, v115
	v_mul_f32_e32 v0, v30, v0
	v_fmac_f32_e32 v19, v15, v0
	v_cvt_pk_bf16_f32 v0, v19, s0
	ds_write_b16 v83, v0 offset:1904
	s_waitcnt vmcnt(0)
; #define LAS __attribute__((address_space(3)))
; #define MFMA16(a, b, c) __builtin_amdgcn_mfma_f32_16x16x32_bf16(a, b, c, 0, 0, 0)
; __device__ __forceinline__ unsigned cvt2(float lo, float hi) { bf16v2_t r = __builtin_convertvector((f32x2){lo, hi}, bf16v2_t); return __builtin_bit_cast(unsigned, r); }
; __device__ __forceinline__ void gmlp_mfma(LAS unsigned char* lds, const unsigned char* R, bf16_t* O, const float* lng, const float* lnb, const float* wsp, const float* bsp, int unit, int tid) {
;     ...
;         for (int i = 0; i < 8; ++i) { const int idx = tid + 512 * i, t = idx >> 5, s0 = (idx & 31) * 4;
;             const f32x4 x = *(const f32x4*)(wsp + (size_t)(g * 128 + t) * 128 + s0);
;             u32x2 o; o.x = cvt2(s0 <= t ? x[0] : 0.f, s0 + 1 <= t ? x[1] : 0.f); o.y = cvt2(s0 + 2 <= t ? x[2] : 0.f, s0 + 3 <= t ? x[3] : 0.f);
;             *(LAS u32x2*)(wt + t * QK_STRIDE + s0 * 2) = o; }
;         __syncthreads();
;         f32x4 acc[8];
; #pragma unroll
;         for (int ct = 0; ct < 8; ++ct) acc[ct] = (f32x4){0.f, 0.f, 0.f, 0.f};
;         for (int ks = 0; ks <= (w >> 1); ++ks) { const bf16x8 bW = LDFRAG(wt, 16 * w + fr, QK_STRIDE, 32 * ks + 8 * fq);
; #pragma unroll
;             for (int ct = 0; ct < 8; ++ct) acc[ct] = MFMA16(LDFRAG(vnt, 16 * ct + fr, QK_STRIDE, 32 * ks + 8 * fq), bW, acc[ct]); }
	v_cndmask_b32_e64 v0, v8, 0, s[44:45]
	v_cndmask_b32_e64 v8, 0, v9, s[46:47]
	v_cvt_pk_bf16_f32 v8, v0, v8
	v_cndmask_b32_e64 v0, v10, 0, s[48:49]
	v_cndmask_b32_e64 v9, v11, 0, s[50:51]
	v_cvt_pk_bf16_f32 v9, v0, v9
	ds_write_b64 v84, v[8:9] offset:34816
	v_add_u32_e32 v8, s36, v71
	v_ashrrev_i32_e32 v9, 31, v8
	v_lshlrev_b64 v[8:9], 9, v[8:9]
	v_lshl_add_u64 v[8:9], v[54:55], 0, v[8:9]
	v_mov_b32_e32 v8, v116
	v_mov_b32_e32 v9, v117
	v_mov_b32_e32 v10, v118
	v_mov_b32_e32 v11, v119
	s_waitcnt vmcnt(0)
	v_cndmask_b32_e64 v0, v8, 0, s[52:53]
	v_cndmask_b32_e64 v8, 0, v9, s[54:55]
	v_cvt_pk_bf16_f32 v8, v0, v8
	v_cndmask_b32_e64 v0, v10, 0, s[56:57]
	v_cndmask_b32_e64 v9, v11, 0, s[58:59]
	v_cvt_pk_bf16_f32 v9, v0, v9
	ds_write_b64 v85, v[8:9] offset:34816
	v_add_u32_e32 v8, s36, v72
	v_ashrrev_i32_e32 v9, 31, v8
	v_lshlrev_b64 v[8:9], 9, v[8:9]
	v_lshl_add_u64 v[8:9], v[54:55], 0, v[8:9]
	v_mov_b32_e32 v8, v120
	v_mov_b32_e32 v9, v121
	v_mov_b32_e32 v10, v122
	v_mov_b32_e32 v11, v123
	s_waitcnt vmcnt(0)
	v_cndmask_b32_e64 v0, v8, 0, s[60:61]
	v_cndmask_b32_e64 v8, 0, v9, s[62:63]
	v_cvt_pk_bf16_f32 v8, v0, v8
	v_cndmask_b32_e64 v0, v10, 0, s[64:65]
	v_cndmask_b32_e64 v9, v11, 0, s[66:67]
	v_cvt_pk_bf16_f32 v9, v0, v9
	ds_write_b64 v86, v[8:9] offset:34816
	v_add_u32_e32 v8, s36, v73
	v_ashrrev_i32_e32 v9, 31, v8
	v_lshlrev_b64 v[8:9], 9, v[8:9]
	v_lshl_add_u64 v[8:9], v[54:55], 0, v[8:9]
	v_mov_b32_e32 v8, v124
	v_mov_b32_e32 v9, v125
	v_mov_b32_e32 v10, v126
	v_mov_b32_e32 v11, v127
	s_waitcnt vmcnt(0)
	v_cndmask_b32_e64 v0, v8, 0, s[68:69]
	v_cndmask_b32_e64 v8, 0, v9, s[70:71]
	v_cvt_pk_bf16_f32 v8, v0, v8
	v_cndmask_b32_e64 v0, v10, 0, s[72:73]
	v_cndmask_b32_e64 v9, v11, 0, s[74:75]
	v_cvt_pk_bf16_f32 v9, v0, v9
	ds_write_b64 v87, v[8:9] offset:34816
	v_add_u32_e32 v8, s36, v74
	v_ashrrev_i32_e32 v9, 31, v8
	v_lshlrev_b64 v[8:9], 9, v[8:9]
	v_lshl_add_u64 v[8:9], v[54:55], 0, v[8:9]
	v_mov_b32_e32 v8, v128
	v_mov_b32_e32 v9, v129
	v_mov_b32_e32 v10, v130
	v_mov_b32_e32 v11, v131
	s_waitcnt vmcnt(0)
	v_cndmask_b32_e64 v0, v8, 0, s[76:77]
	v_cndmask_b32_e64 v8, 0, v9, s[78:79]
	v_cvt_pk_bf16_f32 v8, v0, v8
	v_cndmask_b32_e64 v0, v10, 0, s[80:81]
	v_cndmask_b32_e64 v9, v11, 0, s[82:83]
	v_cvt_pk_bf16_f32 v9, v0, v9
	ds_write_b64 v88, v[8:9] offset:34816
	v_add_u32_e32 v8, s36, v75
	v_ashrrev_i32_e32 v9, 31, v8
	v_lshlrev_b64 v[8:9], 9, v[8:9]
	v_lshl_add_u64 v[8:9], v[54:55], 0, v[8:9]
	v_mov_b32_e32 v8, v132
	v_mov_b32_e32 v9, v133
	v_mov_b32_e32 v10, v134
	v_mov_b32_e32 v11, v135
	s_waitcnt vmcnt(0)
	v_cndmask_b32_e64 v0, v8, 0, s[84:85]
	v_cndmask_b32_e64 v8, 0, v9, s[86:87]
	v_cvt_pk_bf16_f32 v8, v0, v8
	v_cndmask_b32_e64 v0, v10, 0, s[88:89]
	v_cndmask_b32_e64 v9, v11, 0, s[90:91]
	v_cvt_pk_bf16_f32 v9, v0, v9
	ds_write_b64 v89, v[8:9] offset:34816
	v_add_u32_e32 v8, s36, v76
	v_ashrrev_i32_e32 v9, 31, v8
	v_lshlrev_b64 v[8:9], 9, v[8:9]
	v_lshl_add_u64 v[8:9], v[54:55], 0, v[8:9]
	v_mov_b32_e32 v8, v136
	v_mov_b32_e32 v9, v137
	v_mov_b32_e32 v10, v138
	v_mov_b32_e32 v11, v139
	s_waitcnt vmcnt(0)
	v_cndmask_b32_e64 v0, v8, 0, s[92:93]
	v_cndmask_b32_e64 v8, 0, v9, s[94:95]
	v_cvt_pk_bf16_f32 v8, v0, v8
	v_cndmask_b32_e64 v0, v10, 0, s[96:97]
	v_cndmask_b32_e64 v9, v11, 0, s[98:99]
	v_cvt_pk_bf16_f32 v9, v0, v9
	ds_write_b64 v90, v[8:9] offset:34816
	v_add_u32_e32 v8, s36, v77
	v_ashrrev_i32_e32 v9, 31, v8
	v_lshlrev_b64 v[8:9], 9, v[8:9]
	v_lshl_add_u64 v[8:9], v[54:55], 0, v[8:9]
	v_mov_b32_e32 v8, v140
	v_mov_b32_e32 v9, v141
	v_mov_b32_e32 v10, v142
	v_mov_b32_e32 v11, v143
	s_waitcnt vmcnt(0)
	v_cndmask_b32_e64 v0, v8, 0, s[6:7]
	v_cndmask_b32_e64 v8, 0, v9, s[8:9]
	v_cvt_pk_bf16_f32 v8, v0, v8
	v_cndmask_b32_e64 v0, v10, 0, s[10:11]
	v_cndmask_b32_e64 v9, v11, 0, s[12:13]
	v_cvt_pk_bf16_f32 v9, v0, v9
	v_mov_b32_e32 v11, 0
	ds_write_b64 v91, v[8:9] offset:34816
	v_mov_b32_e32 v10, v11
	v_mov_b32_e32 v9, v11
	v_mov_b32_e32 v8, v11
	v_mov_b32_e32 v15, v11
	v_mov_b32_e32 v14, v11
	v_mov_b32_e32 v13, v11
	v_mov_b32_e32 v12, v11
	v_mov_b32_e32 v19, v11
	v_mov_b32_e32 v18, v11
	v_mov_b32_e32 v17, v11
	v_mov_b32_e32 v16, v11
	v_mov_b32_e32 v23, v11
	v_mov_b32_e32 v22, v11
	v_mov_b32_e32 v21, v11
	v_mov_b32_e32 v20, v11
	v_mov_b32_e32 v27, v11
	v_mov_b32_e32 v26, v11
	v_mov_b32_e32 v25, v11
	v_mov_b32_e32 v24, v11
	v_mov_b32_e32 v31, v11
	v_mov_b32_e32 v30, v11
	v_mov_b32_e32 v29, v11
	v_mov_b32_e32 v28, v11
	v_mov_b32_e32 v35, v11
	v_mov_b32_e32 v34, v11
	v_mov_b32_e32 v33, v11
	v_mov_b32_e32 v32, v11
	v_mov_b32_e32 v39, v11
	v_mov_b32_e32 v38, v11
	v_mov_b32_e32 v37, v11
	v_mov_b32_e32 v36, v11
	s_waitcnt lgkmcnt(0)
	s_barrier
	s_cbranch_vccnz .LBB0_150
	v_mov_b32_e32 v8, 0
	v_mov_b32_e32 v0, v79
	v_mov_b32_e32 v57, v51
	s_mov_b32 s2, s40
	v_mov_b32_e32 v9, v8
	v_mov_b32_e32 v10, v8
	v_mov_b32_e32 v11, v8
	v_mov_b32_e32 v36, v8
	v_mov_b32_e32 v37, v8
	v_mov_b32_e32 v38, v8
	v_mov_b32_e32 v39, v8
	v_mov_b32_e32 v32, v8
	v_mov_b32_e32 v33, v8
	v_mov_b32_e32 v34, v8
	v_mov_b32_e32 v35, v8
	v_mov_b32_e32 v28, v8
	v_mov_b32_e32 v29, v8
	v_mov_b32_e32 v30, v8
	v_mov_b32_e32 v31, v8
	v_mov_b32_e32 v24, v8
	v_mov_b32_e32 v25, v8
	v_mov_b32_e32 v26, v8
	v_mov_b32_e32 v27, v8
	v_mov_b32_e32 v20, v8
	v_mov_b32_e32 v21, v8
	v_mov_b32_e32 v22, v8
	v_mov_b32_e32 v23, v8
	v_mov_b32_e32 v16, v8
	v_mov_b32_e32 v17, v8
	v_mov_b32_e32 v18, v8
	v_mov_b32_e32 v19, v8
	v_mov_b32_e32 v12, v8
	v_mov_b32_e32 v13, v8
	v_mov_b32_e32 v14, v8
	v_mov_b32_e32 v15, v8

; #define PG8_STAGE(bufoff, gbase, voff) do { _Pragma("unroll") for (int _i = 0; _i < 2; ++_i) \
;         __builtin_amdgcn_global_load_lds((const unsigned*)((const char*)(gbase) + (voff)[_i]), (PG8_LAS unsigned*)(lds + (bufoff) + ldsw + _i * 8192), 16, 0, 0); } while (0)
; #define PG8_LDA(dst, b, h) do { _Pragma("unroll") for (int m = 0; m < 4; ++m) _Pragma("unroll") for (int k = 0; k < 2; ++k) dst[m][k] = *(const PG8_LAS bf16x8*)(lds + PG8_SA(b, h) + aoff + m * 2048 + k * 1024); } while (0)
; #define PG8_LDB(dst, b, h) do { _Pragma("unroll") for (int n = 0; n < 2; ++n) _Pragma("unroll") for (int k = 0; k < 2; ++k) dst[n][k] = *(const PG8_LAS bf16x8*)(lds + PG8_SB(b, h) + boff + n * 2048 + k * 1024); } while (0)
; #define PG8_MMA(ai, bj, At, Bt) do { __builtin_amdgcn_s_setprio(1); _Pragma("unroll") for (int m = 0; m < 4; ++m) _Pragma("unroll") for (int n = 0; n < 2; ++n) _Pragma("unroll") for (int k = 0; k < 2; ++k) \
;         acc[ai][bj][m][n] = __builtin_amdgcn_mfma_f32_16x16x32_bf16(Bt[n][k], At[m][k], acc[ai][bj][m][n], 0, 0, 0); __builtin_amdgcn_s_setprio(0); } while (0)
; #define PG8_WAIT_V(n) asm volatile("s_waitcnt vmcnt(" #n ")" ::: "memory")
; #define PG8_BAR __builtin_amdgcn_s_barrier()
; template <class Epi, class Sched, bool ALIGN_EPI = false, bool SP2 = false>
; __device__ __forceinline__ void gemm_phase(PG8_LAS unsigned char* lds, const Gemm g, const Sched& S, const Epi& E) {
;     ...
;         for (int t = 0; t < nt; t += 2) {
;             const bool last = (t == nt - 2);
;             const char* a1 = cA + (size_t)(t + 1) * kstep;
;             const char* a2 = last ? nA : cA + (size_t)(t + 2) * kstep; const char* b2 = last ? nB : cB + (size_t)(t + 2) * kstep;
;             const char* a3 = a2 + kstep; const char* b3 = b2 + kstep;
;             if (last && has_next) S.a_ready(nxt);
;             if constexpr (SP2) {
;             PG8_LDB(B0, 0, 0); PG8_LDB(B1, 0, 1); PG8_SCHED; PG8_LDA(At, 0, 0); PG8_STAGE(PG8_SA(1, 1), a1 + hstep, voffA);
;             PG8_WAIT_V(8); PG8_WAIT_L(0); PG8_BAR; PG8_MMA(0, 0, At, B0); PG8_MMA(0, 1, At, B1); PG8_BAR; PG8_SCHED;
;             PG8_LDA(At, 0, 1); PG8_STAGE(PG8_SB(0, 0), b2, voffB); PG8_STAGE(PG8_SB(0, 1), b2 + hstep, voffB); PG8_STAGE(PG8_SA(0, 0), a2, voffA);
;             PG8_WAIT_V(8); PG8_WAIT_L(0); PG8_BAR; PG8_MMA(1, 0, At, B0); PG8_MMA(1, 1, At, B1); PG8_BAR; PG8_SCHED;
.LBB0_165:
	s_add_u32 s16, s8, 0xfffc0080
	s_addc_u32 s17, s9, -1
	s_add_i32 s18, 0, 0x10000
	s_cmp_eq_u32 s55, 12
	s_cselect_b32 s43, s14, s17
	s_cselect_b32 s42, s15, s16
	v_add_u32_e32 v0, s18, v194
	s_cselect_b32 s41, s13, s54
	s_cselect_b32 s40, s25, s53
	s_add_i32 s19, 0, 0x14000
	ds_read_b128 v[136:139], v0
	ds_read_b128 v[140:143], v0 offset:1024
	ds_read_b128 v[144:147], v0 offset:2048
	ds_read_b128 v[148:151], v0 offset:3072
	v_add_u32_e32 v0, s19, v194
	ds_read_b128 v[152:155], v0
	ds_read_b128 v[186:189], v0 offset:1024
	ds_read_b128 v[190:193], v0 offset:2048
	ds_read_b128 v[198:201], v0 offset:3072
	v_lshl_add_u64 v[2:3], s[8:9], 0, v[182:183]
	s_add_i32 m0, s45, 0xc000
	ds_read_b128 v[210:213], v196
	ds_read_b128 v[214:217], v196 offset:1024
	ds_read_b128 v[218:221], v196 offset:2048
	ds_read_b128 v[222:225], v196 offset:3072
	ds_read_b128 v[226:229], v196 offset:4096
	ds_read_b128 v[230:233], v196 offset:5120
	ds_read_b128 v[234:237], v196 offset:6144
	ds_read_b128 v[238:241], v196 offset:7168
	global_load_lds_dwordx4 v[2:3], off
	v_lshl_add_u64 v[2:3], s[8:9], 0, v[184:185]
	s_add_i32 m0, s45, 0xe000
	s_nop 0
	global_load_lds_dwordx4 v[2:3], off
	s_waitcnt vmcnt(8)
	s_waitcnt lgkmcnt(0)
	s_barrier
	s_setprio 1
	s_waitcnt lgkmcnt(0)
	v_mfma_f32_16x16x32_bf16 v[132:135], v[136:139], v[210:213], v[132:135]
	v_mfma_f32_16x16x32_bf16 v[128:131], v[144:147], v[210:213], v[128:131]
	v_mfma_f32_16x16x32_bf16 v[124:127], v[136:139], v[218:221], v[124:127]
	v_mfma_f32_16x16x32_bf16 v[120:123], v[144:147], v[218:221], v[120:123]
	v_mfma_f32_16x16x32_bf16 v[116:119], v[136:139], v[226:229], v[116:119]
	v_mfma_f32_16x16x32_bf16 v[112:115], v[144:147], v[226:229], v[112:115]
	v_mfma_f32_16x16x32_bf16 v[108:111], v[136:139], v[234:237], v[108:111]
	v_mfma_f32_16x16x32_bf16 v[104:107], v[144:147], v[234:237], v[104:107]
	v_mfma_f32_16x16x32_bf16 v[132:135], v[140:143], v[214:217], v[132:135]
	v_mfma_f32_16x16x32_bf16 v[128:131], v[148:151], v[214:217], v[128:131]
	v_mfma_f32_16x16x32_bf16 v[124:127], v[140:143], v[222:225], v[124:127]
	v_mfma_f32_16x16x32_bf16 v[120:123], v[148:151], v[222:225], v[120:123]
	v_mfma_f32_16x16x32_bf16 v[116:119], v[140:143], v[230:233], v[116:119]
	v_mfma_f32_16x16x32_bf16 v[112:115], v[148:151], v[230:233], v[112:115]
	v_mfma_f32_16x16x32_bf16 v[108:111], v[140:143], v[238:241], v[108:111]
	v_mfma_f32_16x16x32_bf16 v[104:107], v[148:151], v[238:241], v[104:107]
	s_setprio 0
	s_setprio 1
	v_mfma_f32_16x16x32_bf16 v[84:87], v[152:155], v[210:213], v[84:87]
	v_mfma_f32_16x16x32_bf16 v[76:79], v[190:193], v[210:213], v[76:79]
	v_mfma_f32_16x16x32_bf16 v[68:71], v[152:155], v[218:221], v[68:71]
	v_mfma_f32_16x16x32_bf16 v[64:67], v[190:193], v[218:221], v[64:67]
	v_mfma_f32_16x16x32_bf16 v[52:55], v[152:155], v[226:229], v[52:55]
	v_mfma_f32_16x16x32_bf16 v[48:51], v[190:193], v[226:229], v[48:51]
	v_mfma_f32_16x16x32_bf16 v[44:47], v[152:155], v[234:237], v[44:47]
	v_mfma_f32_16x16x32_bf16 v[40:43], v[190:193], v[234:237], v[40:43]
	v_mfma_f32_16x16x32_bf16 v[84:87], v[186:189], v[214:217], v[84:87]
	v_mfma_f32_16x16x32_bf16 v[76:79], v[198:201], v[214:217], v[76:79]
	v_mfma_f32_16x16x32_bf16 v[68:71], v[186:189], v[222:225], v[68:71]
	v_mfma_f32_16x16x32_bf16 v[64:67], v[198:201], v[222:225], v[64:67]
	v_mfma_f32_16x16x32_bf16 v[52:55], v[186:189], v[230:233], v[52:55]
	v_mfma_f32_16x16x32_bf16 v[48:51], v[198:201], v[230:233], v[48:51]
	v_mfma_f32_16x16x32_bf16 v[44:47], v[186:189], v[238:241], v[44:47]
	v_mfma_f32_16x16x32_bf16 v[40:43], v[198:201], v[238:241], v[40:43]
	s_setprio 0
	s_barrier
	s_add_i32 s16, s18, s44
	v_lshl_add_u64 v[2:3], s[40:41], 0, v[162:163]
	s_mov_b32 m0, s16
	ds_read_b128 v[210:213], v196 offset:16384
	ds_read_b128 v[214:217], v196 offset:17408
	ds_read_b128 v[218:221], v196 offset:18432
	ds_read_b128 v[222:225], v196 offset:19456
	ds_read_b128 v[226:229], v196 offset:20480
	ds_read_b128 v[230:233], v196 offset:21504
	ds_read_b128 v[234:237], v196 offset:22528
	ds_read_b128 v[238:241], v196 offset:23552
	global_load_lds_dwordx4 v[2:3], off
	s_add_i32 m0, s16, 0x2000
	s_add_u32 s16, s40, 0x40000
	v_lshl_add_u64 v[156:157], s[40:41], 0, v[158:159]
	s_addc_u32 s17, s41, 0
	s_add_i32 s18, s19, s44
	global_load_lds_dwordx4 v[156:157], off
	v_lshl_add_u64 v[242:243], s[16:17], 0, v[162:163]
	s_mov_b32 m0, s18
	v_lshl_add_u64 v[244:245], s[42:43], 0, v[160:161]
	global_load_lds_dwordx4 v[242:243], off
	v_lshl_add_u64 v[242:243], s[16:17], 0, v[158:159]
	s_add_i32 m0, s18, 0x2000
	s_nop 0
	global_load_lds_dwordx4 v[242:243], off
	v_lshl_add_u64 v[242:243], s[42:43], 0, v[178:179]
	s_waitcnt vmcnt(6)
	s_waitcnt lgkmcnt(0)
	s_barrier
; #define PG8_STAGE(bufoff, gbase, voff) do { _Pragma("unroll") for (int _i = 0; _i < 2; ++_i) \
;         __builtin_amdgcn_global_load_lds((const unsigned*)((const char*)(gbase) + (voff)[_i]), (PG8_LAS unsigned*)(lds + (bufoff) + ldsw + _i * 8192), 16, 0, 0); } while (0)
; #define PG8_LDA(dst, b, h) do { _Pragma("unroll") for (int m = 0; m < 4; ++m) _Pragma("unroll") for (int k = 0; k < 2; ++k) dst[m][k] = *(const PG8_LAS bf16x8*)(lds + PG8_SA(b, h) + aoff + m * 2048 + k * 1024); } while (0)
; #define PG8_LDB(dst, b, h) do { _Pragma("unroll") for (int n = 0; n < 2; ++n) _Pragma("unroll") for (int k = 0; k < 2; ++k) dst[n][k] = *(const PG8_LAS bf16x8*)(lds + PG8_SB(b, h) + boff + n * 2048 + k * 1024); } while (0)
; #define PG8_MMA(ai, bj, At, Bt) do { __builtin_amdgcn_s_setprio(1); _Pragma("unroll") for (int m = 0; m < 4; ++m) _Pragma("unroll") for (int n = 0; n < 2; ++n) _Pragma("unroll") for (int k = 0; k < 2; ++k) \
;         acc[ai][bj][m][n] = __builtin_amdgcn_mfma_f32_16x16x32_bf16(Bt[n][k], At[m][k], acc[ai][bj][m][n], 0, 0, 0); __builtin_amdgcn_s_setprio(0); } while (0)
; #define PG8_WAIT_V(n) asm volatile("s_waitcnt vmcnt(" #n ")" ::: "memory")
; #define PG8_WAIT_L(n) asm volatile("s_waitcnt lgkmcnt(" #n ")" ::: "memory")
; #define PG8_BAR __builtin_amdgcn_s_barrier()
; #define PG8_SCHED __builtin_amdgcn_sched_barrier(0)
; template <class Epi, class Sched, bool ALIGN_EPI = false, bool SP2 = false>
; __device__ __forceinline__ void gemm_phase(PG8_LAS unsigned char* lds, const Gemm g, const Sched& S, const Epi& E) {
;     ...
;             PG8_WAIT_V(8); PG8_WAIT_L(0); PG8_BAR; PG8_MMA(0, 0, At, B0); PG8_MMA(0, 1, At, B1); PG8_BAR; PG8_SCHED;
;             PG8_LDA(At, 0, 1); PG8_STAGE(PG8_SB(0, 0), b2, voffB); PG8_STAGE(PG8_SB(0, 1), b2 + hstep, voffB); PG8_STAGE(PG8_SA(0, 0), a2, voffA);
;             PG8_WAIT_V(8); PG8_WAIT_L(0); PG8_BAR; PG8_MMA(1, 0, At, B0); PG8_MMA(1, 1, At, B1); PG8_BAR; PG8_SCHED;
;             PG8_LDB(B0, 1, 0); PG8_LDB(B1, 1, 1); PG8_SCHED; PG8_LDA(At, 1, 0); PG8_STAGE(PG8_SA(0, 1), a2 + hstep, voffA);
;             PG8_WAIT_V(8); PG8_WAIT_L(0); PG8_BAR; PG8_MMA(0, 0, At, B0); PG8_MMA(0, 1, At, B1); PG8_BAR; PG8_SCHED;
	s_setprio 1
	s_waitcnt lgkmcnt(0)
	v_mfma_f32_16x16x32_bf16 v[100:103], v[136:139], v[210:213], v[100:103]
	v_mfma_f32_16x16x32_bf16 v[96:99], v[144:147], v[210:213], v[96:99]
	v_mfma_f32_16x16x32_bf16 v[92:95], v[136:139], v[218:221], v[92:95]
	s_mov_b32 m0, s45
	v_mfma_f32_16x16x32_bf16 v[88:91], v[144:147], v[218:221], v[88:91]
	global_load_lds_dwordx4 v[242:243], off
	v_mfma_f32_16x16x32_bf16 v[80:83], v[136:139], v[226:229], v[80:83]
	v_mfma_f32_16x16x32_bf16 v[72:75], v[144:147], v[226:229], v[72:75]
	v_mfma_f32_16x16x32_bf16 v[60:63], v[136:139], v[234:237], v[60:63]
	v_mfma_f32_16x16x32_bf16 v[56:59], v[144:147], v[234:237], v[56:59]
	v_mfma_f32_16x16x32_bf16 v[100:103], v[140:143], v[214:217], v[100:103]
	v_mfma_f32_16x16x32_bf16 v[96:99], v[148:151], v[214:217], v[96:99]
	v_mfma_f32_16x16x32_bf16 v[92:95], v[140:143], v[222:225], v[92:95]
	s_mov_b32 m0, s46
	v_mfma_f32_16x16x32_bf16 v[88:91], v[148:151], v[222:225], v[88:91]
	global_load_lds_dwordx4 v[244:245], off
	v_mfma_f32_16x16x32_bf16 v[80:83], v[140:143], v[230:233], v[80:83]
	v_mfma_f32_16x16x32_bf16 v[72:75], v[148:151], v[230:233], v[72:75]
	v_mfma_f32_16x16x32_bf16 v[60:63], v[140:143], v[238:241], v[60:63]
	v_mfma_f32_16x16x32_bf16 v[56:59], v[148:151], v[238:241], v[56:59]
	s_setprio 0
	s_setprio 1
	v_mfma_f32_16x16x32_bf16 v[36:39], v[152:155], v[210:213], v[36:39]
	v_mfma_f32_16x16x32_bf16 v[32:35], v[190:193], v[210:213], v[32:35]
	v_mfma_f32_16x16x32_bf16 v[28:31], v[152:155], v[218:221], v[28:31]
	v_mfma_f32_16x16x32_bf16 v[24:27], v[190:193], v[218:221], v[24:27]
	v_mfma_f32_16x16x32_bf16 v[20:23], v[152:155], v[226:229], v[20:23]
	v_mfma_f32_16x16x32_bf16 v[16:19], v[190:193], v[226:229], v[16:19]
	v_mfma_f32_16x16x32_bf16 v[12:15], v[152:155], v[234:237], v[12:15]
	v_mfma_f32_16x16x32_bf16 v[8:11], v[190:193], v[234:237], v[8:11]
	v_mfma_f32_16x16x32_bf16 v[36:39], v[186:189], v[214:217], v[36:39]
	v_mfma_f32_16x16x32_bf16 v[32:35], v[198:201], v[214:217], v[32:35]
	v_mfma_f32_16x16x32_bf16 v[28:31], v[186:189], v[222:225], v[28:31]
	v_mfma_f32_16x16x32_bf16 v[24:27], v[198:201], v[222:225], v[24:27]
	v_mfma_f32_16x16x32_bf16 v[20:23], v[186:189], v[230:233], v[20:23]
	v_mfma_f32_16x16x32_bf16 v[16:19], v[198:201], v[230:233], v[16:19]
	v_mfma_f32_16x16x32_bf16 v[12:15], v[186:189], v[238:241], v[12:15]
	v_mfma_f32_16x16x32_bf16 v[8:11], v[198:201], v[238:241], v[8:11]
	s_setprio 0
	s_barrier
	s_add_i32 s18, 0, 0x18000
	v_add_u32_e32 v0, s18, v194
	ds_read_b128 v[136:139], v0
	ds_read_b128 v[140:143], v0 offset:1024
	ds_read_b128 v[144:147], v0 offset:2048
	ds_read_b128 v[148:151], v0 offset:3072
	v_add_u32_e32 v0, s33, v194
	ds_read_b128 v[152:155], v0
	ds_read_b128 v[186:189], v0 offset:1024
	ds_read_b128 v[190:193], v0 offset:2048
	ds_read_b128 v[198:201], v0 offset:3072
	s_add_u32 s16, s42, 0x40000
	s_addc_u32 s17, s43, 0
	s_mov_b32 m0, s47
	v_lshl_add_u64 v[246:247], s[16:17], 0, v[178:179]
	ds_read_b128 v[210:213], v196 offset:32768
	ds_read_b128 v[214:217], v196 offset:33792
	ds_read_b128 v[218:221], v196 offset:34816
	ds_read_b128 v[222:225], v196 offset:35840
	ds_read_b128 v[226:229], v196 offset:36864
	ds_read_b128 v[230:233], v196 offset:37888
	ds_read_b128 v[234:237], v196 offset:38912
	ds_read_b128 v[238:241], v196 offset:39936
	global_load_lds_dwordx4 v[246:247], off
	v_lshl_add_u64 v[246:247], s[16:17], 0, v[160:161]
	s_mov_b32 m0, s48
	s_nop 0
	global_load_lds_dwordx4 v[246:247], off
	s_waitcnt vmcnt(8)
	s_waitcnt lgkmcnt(0)
	s_barrier
	s_setprio 1
	s_waitcnt lgkmcnt(0)
	v_mfma_f32_16x16x32_bf16 v[132:135], v[136:139], v[210:213], v[132:135]
	v_mfma_f32_16x16x32_bf16 v[128:131], v[144:147], v[210:213], v[128:131]
	v_mfma_f32_16x16x32_bf16 v[124:127], v[136:139], v[218:221], v[124:127]
	v_mfma_f32_16x16x32_bf16 v[120:123], v[144:147], v[218:221], v[120:123]
	v_mfma_f32_16x16x32_bf16 v[116:119], v[136:139], v[226:229], v[116:119]
	v_mfma_f32_16x16x32_bf16 v[112:115], v[144:147], v[226:229], v[112:115]
	v_mfma_f32_16x16x32_bf16 v[108:111], v[136:139], v[234:237], v[108:111]
	v_mfma_f32_16x16x32_bf16 v[104:107], v[144:147], v[234:237], v[104:107]
	v_mfma_f32_16x16x32_bf16 v[132:135], v[140:143], v[214:217], v[132:135]
	v_mfma_f32_16x16x32_bf16 v[128:131], v[148:151], v[214:217], v[128:131]
	v_mfma_f32_16x16x32_bf16 v[124:127], v[140:143], v[222:225], v[124:127]
	v_mfma_f32_16x16x32_bf16 v[120:123], v[148:151], v[222:225], v[120:123]
	v_mfma_f32_16x16x32_bf16 v[116:119], v[140:143], v[230:233], v[116:119]
	v_mfma_f32_16x16x32_bf16 v[112:115], v[148:151], v[230:233], v[112:115]
	v_mfma_f32_16x16x32_bf16 v[108:111], v[140:143], v[238:241], v[108:111]
	v_mfma_f32_16x16x32_bf16 v[104:107], v[148:151], v[238:241], v[104:107]
	s_setprio 0
	s_setprio 1
	v_mfma_f32_16x16x32_bf16 v[84:87], v[152:155], v[210:213], v[84:87]
	v_mfma_f32_16x16x32_bf16 v[76:79], v[190:193], v[210:213], v[76:79]
	v_mfma_f32_16x16x32_bf16 v[68:71], v[152:155], v[218:221], v[68:71]
	v_mfma_f32_16x16x32_bf16 v[64:67], v[190:193], v[218:221], v[64:67]
	v_mfma_f32_16x16x32_bf16 v[52:55], v[152:155], v[226:229], v[52:55]
	v_mfma_f32_16x16x32_bf16 v[48:51], v[190:193], v[226:229], v[48:51]
	v_mfma_f32_16x16x32_bf16 v[44:47], v[152:155], v[234:237], v[44:47]
	v_mfma_f32_16x16x32_bf16 v[40:43], v[190:193], v[234:237], v[40:43]
	v_mfma_f32_16x16x32_bf16 v[84:87], v[186:189], v[214:217], v[84:87]
	v_mfma_f32_16x16x32_bf16 v[76:79], v[198:201], v[214:217], v[76:79]
	v_mfma_f32_16x16x32_bf16 v[68:71], v[186:189], v[222:225], v[68:71]
	v_mfma_f32_16x16x32_bf16 v[64:67], v[198:201], v[222:225], v[64:67]
	v_mfma_f32_16x16x32_bf16 v[52:55], v[186:189], v[230:233], v[52:55]
	v_mfma_f32_16x16x32_bf16 v[48:51], v[198:201], v[230:233], v[48:51]
	v_mfma_f32_16x16x32_bf16 v[44:47], v[186:189], v[238:241], v[44:47]
	v_mfma_f32_16x16x32_bf16 v[40:43], v[198:201], v[238:241], v[40:43]
	s_setprio 0
	s_barrier
; #define PG8_STAGE(bufoff, gbase, voff) do { _Pragma("unroll") for (int _i = 0; _i < 2; ++_i) \
;         __builtin_amdgcn_global_load_lds((const unsigned*)((const char*)(gbase) + (voff)[_i]), (PG8_LAS unsigned*)(lds + (bufoff) + ldsw + _i * 8192), 16, 0, 0); } while (0)
; #define PG8_LDA(dst, b, h) do { _Pragma("unroll") for (int m = 0; m < 4; ++m) _Pragma("unroll") for (int k = 0; k < 2; ++k) dst[m][k] = *(const PG8_LAS bf16x8*)(lds + PG8_SA(b, h) + aoff + m * 2048 + k * 1024); } while (0)
; #define PG8_LDB(dst, b, h) do { _Pragma("unroll") for (int n = 0; n < 2; ++n) _Pragma("unroll") for (int k = 0; k < 2; ++k) dst[n][k] = *(const PG8_LAS bf16x8*)(lds + PG8_SB(b, h) + boff + n * 2048 + k * 1024); } while (0)
; #define PG8_MMA(ai, bj, At, Bt) do { __builtin_amdgcn_s_setprio(1); _Pragma("unroll") for (int m = 0; m < 4; ++m) _Pragma("unroll") for (int n = 0; n < 2; ++n) _Pragma("unroll") for (int k = 0; k < 2; ++k) \
;         acc[ai][bj][m][n] = __builtin_amdgcn_mfma_f32_16x16x32_bf16(Bt[n][k], At[m][k], acc[ai][bj][m][n], 0, 0, 0); __builtin_amdgcn_s_setprio(0); } while (0)
; #define PG8_WAIT_V(n) asm volatile("s_waitcnt vmcnt(" #n ")" ::: "memory")
; #define PG8_WAIT_L(n) asm volatile("s_waitcnt lgkmcnt(" #n ")" ::: "memory")
; #define PG8_BAR __builtin_amdgcn_s_barrier()
; #define PG8_SCHED __builtin_amdgcn_sched_barrier(0)
; template <class Epi, class Sched, bool ALIGN_EPI = false, bool SP2 = false>
; __device__ __forceinline__ void gemm_phase(PG8_LAS unsigned char* lds, const Gemm g, const Sched& S, const Epi& E) {
;     ...
;             PG8_LDB(B0, 1, 0); PG8_LDB(B1, 1, 1); PG8_SCHED; PG8_LDA(At, 1, 0); PG8_STAGE(PG8_SA(0, 1), a2 + hstep, voffA);
;             PG8_WAIT_V(8); PG8_WAIT_L(0); PG8_BAR; PG8_MMA(0, 0, At, B0); PG8_MMA(0, 1, At, B1); PG8_BAR; PG8_SCHED;
;             PG8_LDA(At, 1, 1); PG8_STAGE(PG8_SB(1, 0), b3, voffB); PG8_STAGE(PG8_SB(1, 1), b3 + hstep, voffB); PG8_STAGE(PG8_SA(1, 0), a3, voffA);
;             PG8_WAIT_V(8); PG8_WAIT_L(0); PG8_BAR; PG8_MMA(1, 0, At, B0); PG8_MMA(1, 1, At, B1); PG8_BAR; PG8_SCHED;
	s_add_i32 s16, s18, s44
	v_lshl_add_u64 v[2:3], v[2:3], 0, s[20:21]
	s_mov_b32 m0, s16
	ds_read_b128 v[210:213], v196 offset:49152
	ds_read_b128 v[214:217], v196 offset:50176
	ds_read_b128 v[218:221], v196 offset:51200
	ds_read_b128 v[222:225], v196 offset:52224
	ds_read_b128 v[226:229], v196 offset:53248
	ds_read_b128 v[230:233], v196 offset:54272
	ds_read_b128 v[234:237], v196 offset:55296
	ds_read_b128 v[238:241], v196 offset:56320
	global_load_lds_dwordx4 v[2:3], off
	s_add_i32 m0, s16, 0x2000
	s_add_u32 s16, s40, 0x40080
	v_lshl_add_u64 v[2:3], v[156:157], 0, s[20:21]
	s_addc_u32 s17, s41, 0
	s_add_i32 s18, s33, s44
	global_load_lds_dwordx4 v[2:3], off
	v_lshl_add_u64 v[2:3], s[16:17], 0, v[162:163]
	s_mov_b32 m0, s18
	s_nop 0
	global_load_lds_dwordx4 v[2:3], off
	v_lshl_add_u64 v[2:3], s[16:17], 0, v[158:159]
	s_add_i32 m0, s18, 0x2000
	s_nop 0
	global_load_lds_dwordx4 v[2:3], off
	v_lshl_add_u64 v[2:3], v[242:243], 0, s[20:21]
	v_lshl_add_u64 v[244:245], v[244:245], 0, s[20:21]
	s_waitcnt vmcnt(6)
	s_waitcnt lgkmcnt(0)
	s_barrier
	s_setprio 1
	s_waitcnt lgkmcnt(0)
	v_mfma_f32_16x16x32_bf16 v[100:103], v[136:139], v[210:213], v[100:103]
	v_mfma_f32_16x16x32_bf16 v[96:99], v[144:147], v[210:213], v[96:99]
	v_mfma_f32_16x16x32_bf16 v[92:95], v[136:139], v[218:221], v[92:95]
	s_mov_b32 m0, s49
	v_mfma_f32_16x16x32_bf16 v[88:91], v[144:147], v[218:221], v[88:91]
	global_load_lds_dwordx4 v[2:3], off
	v_mfma_f32_16x16x32_bf16 v[80:83], v[136:139], v[226:229], v[80:83]
	v_mfma_f32_16x16x32_bf16 v[72:75], v[144:147], v[226:229], v[72:75]
	v_mfma_f32_16x16x32_bf16 v[60:63], v[136:139], v[234:237], v[60:63]
	v_mfma_f32_16x16x32_bf16 v[56:59], v[144:147], v[234:237], v[56:59]
	v_mfma_f32_16x16x32_bf16 v[100:103], v[140:143], v[214:217], v[100:103]
	v_mfma_f32_16x16x32_bf16 v[96:99], v[148:151], v[214:217], v[96:99]
	v_mfma_f32_16x16x32_bf16 v[92:95], v[140:143], v[222:225], v[92:95]
	s_mov_b32 m0, s50
	v_mfma_f32_16x16x32_bf16 v[88:91], v[148:151], v[222:225], v[88:91]
	global_load_lds_dwordx4 v[244:245], off
	v_mfma_f32_16x16x32_bf16 v[80:83], v[140:143], v[230:233], v[80:83]
	v_mfma_f32_16x16x32_bf16 v[72:75], v[148:151], v[230:233], v[72:75]
	v_mfma_f32_16x16x32_bf16 v[60:63], v[140:143], v[238:241], v[60:63]
	v_mfma_f32_16x16x32_bf16 v[56:59], v[148:151], v[238:241], v[56:59]
	s_setprio 0
	s_setprio 1
	v_mfma_f32_16x16x32_bf16 v[36:39], v[152:155], v[210:213], v[36:39]
	v_mfma_f32_16x16x32_bf16 v[32:35], v[190:193], v[210:213], v[32:35]
	v_mfma_f32_16x16x32_bf16 v[28:31], v[152:155], v[218:221], v[28:31]
	v_mfma_f32_16x16x32_bf16 v[24:27], v[190:193], v[218:221], v[24:27]
	v_mfma_f32_16x16x32_bf16 v[20:23], v[152:155], v[226:229], v[20:23]
	v_mfma_f32_16x16x32_bf16 v[16:19], v[190:193], v[226:229], v[16:19]
	v_mfma_f32_16x16x32_bf16 v[12:15], v[152:155], v[234:237], v[12:15]
	v_mfma_f32_16x16x32_bf16 v[8:11], v[190:193], v[234:237], v[8:11]
	v_mfma_f32_16x16x32_bf16 v[36:39], v[186:189], v[214:217], v[36:39]
	v_mfma_f32_16x16x32_bf16 v[32:35], v[198:201], v[214:217], v[32:35]
	v_mfma_f32_16x16x32_bf16 v[28:31], v[186:189], v[222:225], v[28:31]
	v_mfma_f32_16x16x32_bf16 v[24:27], v[198:201], v[222:225], v[24:27]
	v_mfma_f32_16x16x32_bf16 v[20:23], v[186:189], v[230:233], v[20:23]
	v_mfma_f32_16x16x32_bf16 v[16:19], v[198:201], v[230:233], v[16:19]
	v_mfma_f32_16x16x32_bf16 v[12:15], v[186:189], v[238:241], v[12:15]
	v_mfma_f32_16x16x32_bf16 v[8:11], v[198:201], v[238:241], v[8:11]
	s_setprio 0
	s_barrier
	s_add_i32 s55, s55, 2
	s_add_u32 s8, s8, 0x100
	s_addc_u32 s9, s9, 0
	s_add_u32 s53, s53, 0x100
	s_addc_u32 s54, s54, 0
	s_cmp_gt_u32 s55, 13
	s_cbranch_scc0 .LBB0_165
	s_and_b64 vcc, exec, s[10:11]
	s_cbranch_vccz .LBB0_168
	s_barrier
	s_setprio 1

; #define PG8_STAGE(bufoff, gbase, voff) do { _Pragma("unroll") for (int _i = 0; _i < 2; ++_i) \
;         __builtin_amdgcn_global_load_lds((const unsigned*)((const char*)(gbase) + (voff)[_i]), (PG8_LAS unsigned*)(lds + (bufoff) + ldsw + _i * 8192), 16, 0, 0); } while (0)
; #define PG8_LDA(dst, b, h) do { _Pragma("unroll") for (int m = 0; m < 4; ++m) _Pragma("unroll") for (int k = 0; k < 2; ++k) dst[m][k] = *(const PG8_LAS bf16x8*)(lds + PG8_SA(b, h) + aoff + m * 2048 + k * 1024); } while (0)
; #define PG8_LDB(dst, b, h) do { _Pragma("unroll") for (int n = 0; n < 2; ++n) _Pragma("unroll") for (int k = 0; k < 2; ++k) dst[n][k] = *(const PG8_LAS bf16x8*)(lds + PG8_SB(b, h) + boff + n * 2048 + k * 1024); } while (0)
; #define PG8_MMA(ai, bj, At, Bt) do { __builtin_amdgcn_s_setprio(1); _Pragma("unroll") for (int m = 0; m < 4; ++m) _Pragma("unroll") for (int n = 0; n < 2; ++n) _Pragma("unroll") for (int k = 0; k < 2; ++k) \
;         acc[ai][bj][m][n] = __builtin_amdgcn_mfma_f32_16x16x32_bf16(Bt[n][k], At[m][k], acc[ai][bj][m][n], 0, 0, 0); __builtin_amdgcn_s_setprio(0); } while (0)
; #define PG8_WAIT_V(n) asm volatile("s_waitcnt vmcnt(" #n ")" ::: "memory")
; #define PG8_BAR __builtin_amdgcn_s_barrier()
; template <class Epi, class Sched, bool ALIGN_EPI = false, bool SP2 = false>
; __device__ __forceinline__ void gemm_phase(PG8_LAS unsigned char* lds, const Gemm g, const Sched& S, const Epi& E) {
;     ...
;         for (int t = 0; t < nt; t += 2) {
;             const bool last = (t == nt - 2);
;             const char* a1 = cA + (size_t)(t + 1) * kstep;
;             const char* a2 = last ? nA : cA + (size_t)(t + 2) * kstep; const char* b2 = last ? nB : cB + (size_t)(t + 2) * kstep;
;             const char* a3 = a2 + kstep; const char* b3 = b2 + kstep;
;             if (last && has_next) S.a_ready(nxt);
;             if constexpr (SP2) {
;             PG8_LDB(B0, 0, 0); PG8_LDB(B1, 0, 1); PG8_SCHED; PG8_LDA(At, 0, 0); PG8_STAGE(PG8_SA(1, 1), a1 + hstep, voffA);
;             PG8_WAIT_V(8); PG8_WAIT_L(0); PG8_BAR; PG8_MMA(0, 0, At, B0); PG8_MMA(0, 1, At, B1); PG8_BAR; PG8_SCHED;
;             PG8_LDA(At, 0, 1); PG8_STAGE(PG8_SB(0, 0), b2, voffB); PG8_STAGE(PG8_SB(0, 1), b2 + hstep, voffB); PG8_STAGE(PG8_SA(0, 0), a2, voffA);
;             PG8_WAIT_V(8); PG8_WAIT_L(0); PG8_BAR; PG8_MMA(1, 0, At, B0); PG8_MMA(1, 1, At, B1); PG8_BAR; PG8_SCHED;
.LBB0_203:
	s_add_i32 s36, s28, 2
	s_add_u32 s16, s24, 0x80
	s_addc_u32 s17, s25, 0
	s_add_i32 s18, 0, 0x10000
	s_cmp_eq_u32 s60, s28
	s_cselect_b32 s29, s3, s17
	s_cselect_b32 s28, s2, s16
	v_add_u32_e32 v137, s18, v200
	s_cselect_b32 s17, s9, s35
	s_cselect_b32 s16, s8, s23
	s_add_i32 s19, 0, 0x14000
	ds_read_b128 v[144:147], v137
	ds_read_b128 v[148:151], v137 offset:1024
	ds_read_b128 v[152:155], v137 offset:2048
	ds_read_b128 v[156:159], v137 offset:3072
	v_add_u32_e32 v137, s19, v200
	ds_read_b128 v[160:163], v137
	ds_read_b128 v[178:181], v137 offset:1024
	ds_read_b128 v[182:185], v137 offset:2048
	ds_read_b128 v[186:189], v137 offset:3072
	v_lshl_add_u64 v[198:199], s[24:25], 0, v[140:141]
	s_add_i32 m0, s52, 0xc000
	ds_read_b128 v[190:193], v210
	ds_read_b128 v[194:197], v210 offset:1024
	ds_read_b128 v[212:215], v210 offset:2048
	ds_read_b128 v[216:219], v210 offset:3072
	ds_read_b128 v[220:223], v210 offset:4096
	ds_read_b128 v[224:227], v210 offset:5120
	ds_read_b128 v[228:231], v210 offset:6144
	ds_read_b128 v[232:235], v210 offset:7168
	global_load_lds_dwordx4 v[198:199], off
	v_lshl_add_u64 v[198:199], s[24:25], 0, v[142:143]
	s_add_i32 m0, s52, 0xe000
	s_nop 0
	global_load_lds_dwordx4 v[198:199], off
	s_waitcnt vmcnt(8)
	s_waitcnt lgkmcnt(0)
	s_barrier
	s_setprio 1
	s_waitcnt lgkmcnt(0)
	v_mfma_f32_16x16x32_bf16 v[132:135], v[144:147], v[190:193], v[132:135]
	v_mfma_f32_16x16x32_bf16 v[128:131], v[152:155], v[190:193], v[128:131]
	v_mfma_f32_16x16x32_bf16 v[116:119], v[144:147], v[212:215], v[116:119]
	v_mfma_f32_16x16x32_bf16 v[112:115], v[152:155], v[212:215], v[112:115]
	v_mfma_f32_16x16x32_bf16 v[100:103], v[144:147], v[220:223], v[100:103]
	v_mfma_f32_16x16x32_bf16 v[96:99], v[152:155], v[220:223], v[96:99]
	v_mfma_f32_16x16x32_bf16 v[84:87], v[144:147], v[228:231], v[84:87]
	v_mfma_f32_16x16x32_bf16 v[80:83], v[152:155], v[228:231], v[80:83]
	v_mfma_f32_16x16x32_bf16 v[132:135], v[148:151], v[194:197], v[132:135]
	v_mfma_f32_16x16x32_bf16 v[128:131], v[156:159], v[194:197], v[128:131]
	v_mfma_f32_16x16x32_bf16 v[116:119], v[148:151], v[216:219], v[116:119]
	v_mfma_f32_16x16x32_bf16 v[112:115], v[156:159], v[216:219], v[112:115]
	v_mfma_f32_16x16x32_bf16 v[100:103], v[148:151], v[224:227], v[100:103]
	v_mfma_f32_16x16x32_bf16 v[96:99], v[156:159], v[224:227], v[96:99]
	v_mfma_f32_16x16x32_bf16 v[84:87], v[148:151], v[232:235], v[84:87]
	v_mfma_f32_16x16x32_bf16 v[80:83], v[156:159], v[232:235], v[80:83]
	s_setprio 0
	s_setprio 1
	v_mfma_f32_16x16x32_bf16 v[124:127], v[160:163], v[190:193], v[124:127]
	v_mfma_f32_16x16x32_bf16 v[120:123], v[182:185], v[190:193], v[120:123]
	v_mfma_f32_16x16x32_bf16 v[108:111], v[160:163], v[212:215], v[108:111]
	v_mfma_f32_16x16x32_bf16 v[104:107], v[182:185], v[212:215], v[104:107]
	v_mfma_f32_16x16x32_bf16 v[92:95], v[160:163], v[220:223], v[92:95]
	v_mfma_f32_16x16x32_bf16 v[88:91], v[182:185], v[220:223], v[88:91]
	v_mfma_f32_16x16x32_bf16 v[76:79], v[160:163], v[228:231], v[76:79]
	v_mfma_f32_16x16x32_bf16 v[72:75], v[182:185], v[228:231], v[72:75]
	v_mfma_f32_16x16x32_bf16 v[124:127], v[178:181], v[194:197], v[124:127]
	v_mfma_f32_16x16x32_bf16 v[120:123], v[186:189], v[194:197], v[120:123]
	v_mfma_f32_16x16x32_bf16 v[108:111], v[178:181], v[216:219], v[108:111]
	v_mfma_f32_16x16x32_bf16 v[104:107], v[186:189], v[216:219], v[104:107]
	v_mfma_f32_16x16x32_bf16 v[92:95], v[178:181], v[224:227], v[92:95]
	v_mfma_f32_16x16x32_bf16 v[88:91], v[186:189], v[224:227], v[88:91]
	v_mfma_f32_16x16x32_bf16 v[76:79], v[178:181], v[232:235], v[76:79]
	v_mfma_f32_16x16x32_bf16 v[72:75], v[186:189], v[232:235], v[72:75]
	s_setprio 0
	s_barrier
	s_add_i32 s18, s18, s41
	v_lshl_add_u64 v[198:199], s[16:17], 0, v[0:1]
	s_mov_b32 m0, s18
	ds_read_b128 v[190:193], v210 offset:16384
	ds_read_b128 v[194:197], v210 offset:17408
	ds_read_b128 v[212:215], v210 offset:18432
	ds_read_b128 v[216:219], v210 offset:19456
	ds_read_b128 v[220:223], v210 offset:20480
	ds_read_b128 v[224:227], v210 offset:21504
	ds_read_b128 v[228:231], v210 offset:22528
	ds_read_b128 v[232:235], v210 offset:23552
	global_load_lds_dwordx4 v[198:199], off
	s_add_i32 m0, s18, 0x2000
	v_lshl_add_u64 v[236:237], s[16:17], 0, v[2:3]
	s_add_u32 s16, s16, s12
	s_addc_u32 s17, s17, 0
	s_add_i32 s18, s19, s41
	global_load_lds_dwordx4 v[236:237], off
	v_lshl_add_u64 v[238:239], s[16:17], 0, v[0:1]
	s_mov_b32 m0, s18
	v_lshl_add_u64 v[240:241], s[16:17], 0, v[2:3]
	global_load_lds_dwordx4 v[238:239], off
	s_add_i32 m0, s18, 0x2000
	v_lshl_add_u64 v[242:243], s[28:29], 0, v[0:1]
	global_load_lds_dwordx4 v[240:241], off
	v_lshl_add_u64 v[244:245], s[28:29], 0, v[2:3]
	s_waitcnt vmcnt(6)
	s_waitcnt lgkmcnt(0)
	s_barrier
; #define PG8_STAGE(bufoff, gbase, voff) do { _Pragma("unroll") for (int _i = 0; _i < 2; ++_i) \
;         __builtin_amdgcn_global_load_lds((const unsigned*)((const char*)(gbase) + (voff)[_i]), (PG8_LAS unsigned*)(lds + (bufoff) + ldsw + _i * 8192), 16, 0, 0); } while (0)
; #define PG8_LDA(dst, b, h) do { _Pragma("unroll") for (int m = 0; m < 4; ++m) _Pragma("unroll") for (int k = 0; k < 2; ++k) dst[m][k] = *(const PG8_LAS bf16x8*)(lds + PG8_SA(b, h) + aoff + m * 2048 + k * 1024); } while (0)
; #define PG8_LDB(dst, b, h) do { _Pragma("unroll") for (int n = 0; n < 2; ++n) _Pragma("unroll") for (int k = 0; k < 2; ++k) dst[n][k] = *(const PG8_LAS bf16x8*)(lds + PG8_SB(b, h) + boff + n * 2048 + k * 1024); } while (0)
; #define PG8_MMA(ai, bj, At, Bt) do { __builtin_amdgcn_s_setprio(1); _Pragma("unroll") for (int m = 0; m < 4; ++m) _Pragma("unroll") for (int n = 0; n < 2; ++n) _Pragma("unroll") for (int k = 0; k < 2; ++k) \
;         acc[ai][bj][m][n] = __builtin_amdgcn_mfma_f32_16x16x32_bf16(Bt[n][k], At[m][k], acc[ai][bj][m][n], 0, 0, 0); __builtin_amdgcn_s_setprio(0); } while (0)
; #define PG8_WAIT_V(n) asm volatile("s_waitcnt vmcnt(" #n ")" ::: "memory")
; #define PG8_WAIT_L(n) asm volatile("s_waitcnt lgkmcnt(" #n ")" ::: "memory")
; #define PG8_BAR __builtin_amdgcn_s_barrier()
; #define PG8_SCHED __builtin_amdgcn_sched_barrier(0)
; template <class Epi, class Sched, bool ALIGN_EPI = false, bool SP2 = false>
; __device__ __forceinline__ void gemm_phase(PG8_LAS unsigned char* lds, const Gemm g, const Sched& S, const Epi& E) {
;     ...
;             PG8_WAIT_V(8); PG8_WAIT_L(0); PG8_BAR; PG8_MMA(0, 0, At, B0); PG8_MMA(0, 1, At, B1); PG8_BAR; PG8_SCHED;
;             PG8_LDA(At, 0, 1); PG8_STAGE(PG8_SB(0, 0), b2, voffB); PG8_STAGE(PG8_SB(0, 1), b2 + hstep, voffB); PG8_STAGE(PG8_SA(0, 0), a2, voffA);
;             PG8_WAIT_V(8); PG8_WAIT_L(0); PG8_BAR; PG8_MMA(1, 0, At, B0); PG8_MMA(1, 1, At, B1); PG8_BAR; PG8_SCHED;
;             PG8_LDB(B0, 1, 0); PG8_LDB(B1, 1, 1); PG8_SCHED; PG8_LDA(At, 1, 0); PG8_STAGE(PG8_SA(0, 1), a2 + hstep, voffA);
;             PG8_WAIT_V(8); PG8_WAIT_L(0); PG8_BAR; PG8_MMA(0, 0, At, B0); PG8_MMA(0, 1, At, B1); PG8_BAR; PG8_SCHED;
	s_setprio 1
	s_waitcnt lgkmcnt(0)
	v_mfma_f32_16x16x32_bf16 v[68:71], v[144:147], v[190:193], v[68:71]
	v_mfma_f32_16x16x32_bf16 v[64:67], v[152:155], v[190:193], v[64:67]
	v_mfma_f32_16x16x32_bf16 v[52:55], v[144:147], v[212:215], v[52:55]
	s_mov_b32 m0, s52
	v_mfma_f32_16x16x32_bf16 v[48:51], v[152:155], v[212:215], v[48:51]
	global_load_lds_dwordx4 v[242:243], off
	v_mfma_f32_16x16x32_bf16 v[36:39], v[144:147], v[220:223], v[36:39]
	v_mfma_f32_16x16x32_bf16 v[32:35], v[152:155], v[220:223], v[32:35]
	v_mfma_f32_16x16x32_bf16 v[20:23], v[144:147], v[228:231], v[20:23]
	v_mfma_f32_16x16x32_bf16 v[16:19], v[152:155], v[228:231], v[16:19]
	v_mfma_f32_16x16x32_bf16 v[68:71], v[148:151], v[194:197], v[68:71]
	v_mfma_f32_16x16x32_bf16 v[64:67], v[156:159], v[194:197], v[64:67]
	v_mfma_f32_16x16x32_bf16 v[52:55], v[148:151], v[216:219], v[52:55]
	s_mov_b32 m0, s53
	v_mfma_f32_16x16x32_bf16 v[48:51], v[156:159], v[216:219], v[48:51]
	global_load_lds_dwordx4 v[244:245], off
	v_mfma_f32_16x16x32_bf16 v[36:39], v[148:151], v[224:227], v[36:39]
	v_mfma_f32_16x16x32_bf16 v[32:35], v[156:159], v[224:227], v[32:35]
	v_mfma_f32_16x16x32_bf16 v[20:23], v[148:151], v[232:235], v[20:23]
	v_mfma_f32_16x16x32_bf16 v[16:19], v[156:159], v[232:235], v[16:19]
	s_setprio 0
	s_setprio 1
	v_mfma_f32_16x16x32_bf16 v[60:63], v[160:163], v[190:193], v[60:63]
	v_mfma_f32_16x16x32_bf16 v[56:59], v[182:185], v[190:193], v[56:59]
	v_mfma_f32_16x16x32_bf16 v[44:47], v[160:163], v[212:215], v[44:47]
	v_mfma_f32_16x16x32_bf16 v[40:43], v[182:185], v[212:215], v[40:43]
	v_mfma_f32_16x16x32_bf16 v[28:31], v[160:163], v[220:223], v[28:31]
	v_mfma_f32_16x16x32_bf16 v[24:27], v[182:185], v[220:223], v[24:27]
	v_mfma_f32_16x16x32_bf16 v[12:15], v[160:163], v[228:231], v[12:15]
	v_mfma_f32_16x16x32_bf16 v[8:11], v[182:185], v[228:231], v[8:11]
	v_mfma_f32_16x16x32_bf16 v[60:63], v[178:181], v[194:197], v[60:63]
	v_mfma_f32_16x16x32_bf16 v[56:59], v[186:189], v[194:197], v[56:59]
	v_mfma_f32_16x16x32_bf16 v[44:47], v[178:181], v[216:219], v[44:47]
	v_mfma_f32_16x16x32_bf16 v[40:43], v[186:189], v[216:219], v[40:43]
	v_mfma_f32_16x16x32_bf16 v[28:31], v[178:181], v[224:227], v[28:31]
	v_mfma_f32_16x16x32_bf16 v[24:27], v[186:189], v[224:227], v[24:27]
	v_mfma_f32_16x16x32_bf16 v[12:15], v[178:181], v[232:235], v[12:15]
	v_mfma_f32_16x16x32_bf16 v[8:11], v[186:189], v[232:235], v[8:11]
	s_setprio 0
	s_barrier
	s_add_i32 s18, 0, 0x18000
	v_add_u32_e32 v137, s18, v200
	ds_read_b128 v[144:147], v137
	ds_read_b128 v[148:151], v137 offset:1024
	ds_read_b128 v[152:155], v137 offset:2048
	ds_read_b128 v[156:159], v137 offset:3072
	v_add_u32_e32 v137, s33, v200
	ds_read_b128 v[160:163], v137
	ds_read_b128 v[178:181], v137 offset:1024
	ds_read_b128 v[182:185], v137 offset:2048
	ds_read_b128 v[186:189], v137 offset:3072
	s_add_u32 s16, s28, s12
	s_addc_u32 s17, s29, 0
	s_mov_b32 m0, s54
	v_lshl_add_u64 v[246:247], s[16:17], 0, v[0:1]
	ds_read_b128 v[190:193], v210 offset:32768
	ds_read_b128 v[194:197], v210 offset:33792
	ds_read_b128 v[212:215], v210 offset:34816
	ds_read_b128 v[216:219], v210 offset:35840
	ds_read_b128 v[220:223], v210 offset:36864
	ds_read_b128 v[224:227], v210 offset:37888
	ds_read_b128 v[228:231], v210 offset:38912
	ds_read_b128 v[232:235], v210 offset:39936
	global_load_lds_dwordx4 v[246:247], off
	v_lshl_add_u64 v[246:247], s[16:17], 0, v[2:3]
	s_mov_b32 m0, s55
	s_nop 0
	global_load_lds_dwordx4 v[246:247], off
	s_waitcnt vmcnt(8)
	s_waitcnt lgkmcnt(0)
	s_barrier
	s_setprio 1
	s_waitcnt lgkmcnt(0)
	v_mfma_f32_16x16x32_bf16 v[132:135], v[144:147], v[190:193], v[132:135]
	v_mfma_f32_16x16x32_bf16 v[128:131], v[152:155], v[190:193], v[128:131]
	v_mfma_f32_16x16x32_bf16 v[116:119], v[144:147], v[212:215], v[116:119]
	v_mfma_f32_16x16x32_bf16 v[112:115], v[152:155], v[212:215], v[112:115]
	v_mfma_f32_16x16x32_bf16 v[100:103], v[144:147], v[220:223], v[100:103]
	v_mfma_f32_16x16x32_bf16 v[96:99], v[152:155], v[220:223], v[96:99]
	v_mfma_f32_16x16x32_bf16 v[84:87], v[144:147], v[228:231], v[84:87]
	v_mfma_f32_16x16x32_bf16 v[80:83], v[152:155], v[228:231], v[80:83]
	v_mfma_f32_16x16x32_bf16 v[132:135], v[148:151], v[194:197], v[132:135]
	v_mfma_f32_16x16x32_bf16 v[128:131], v[156:159], v[194:197], v[128:131]
	v_mfma_f32_16x16x32_bf16 v[116:119], v[148:151], v[216:219], v[116:119]
	v_mfma_f32_16x16x32_bf16 v[112:115], v[156:159], v[216:219], v[112:115]
	v_mfma_f32_16x16x32_bf16 v[100:103], v[148:151], v[224:227], v[100:103]
	v_mfma_f32_16x16x32_bf16 v[96:99], v[156:159], v[224:227], v[96:99]
	v_mfma_f32_16x16x32_bf16 v[84:87], v[148:151], v[232:235], v[84:87]
	v_mfma_f32_16x16x32_bf16 v[80:83], v[156:159], v[232:235], v[80:83]
	s_setprio 0
	s_setprio 1
	v_mfma_f32_16x16x32_bf16 v[124:127], v[160:163], v[190:193], v[124:127]
	v_mfma_f32_16x16x32_bf16 v[120:123], v[182:185], v[190:193], v[120:123]
	v_mfma_f32_16x16x32_bf16 v[108:111], v[160:163], v[212:215], v[108:111]
	v_mfma_f32_16x16x32_bf16 v[104:107], v[182:185], v[212:215], v[104:107]
	v_mfma_f32_16x16x32_bf16 v[92:95], v[160:163], v[220:223], v[92:95]
	v_mfma_f32_16x16x32_bf16 v[88:91], v[182:185], v[220:223], v[88:91]
	v_mfma_f32_16x16x32_bf16 v[76:79], v[160:163], v[228:231], v[76:79]
	v_mfma_f32_16x16x32_bf16 v[72:75], v[182:185], v[228:231], v[72:75]
	v_mfma_f32_16x16x32_bf16 v[124:127], v[178:181], v[194:197], v[124:127]
	v_mfma_f32_16x16x32_bf16 v[120:123], v[186:189], v[194:197], v[120:123]
	v_mfma_f32_16x16x32_bf16 v[108:111], v[178:181], v[216:219], v[108:111]
	v_mfma_f32_16x16x32_bf16 v[104:107], v[186:189], v[216:219], v[104:107]
	v_mfma_f32_16x16x32_bf16 v[92:95], v[178:181], v[224:227], v[92:95]
	v_mfma_f32_16x16x32_bf16 v[88:91], v[186:189], v[224:227], v[88:91]
	v_mfma_f32_16x16x32_bf16 v[76:79], v[178:181], v[232:235], v[76:79]
	v_mfma_f32_16x16x32_bf16 v[72:75], v[186:189], v[232:235], v[72:75]
	s_setprio 0
	s_barrier
; #define PG8_STAGE(bufoff, gbase, voff) do { _Pragma("unroll") for (int _i = 0; _i < 2; ++_i) \
;         __builtin_amdgcn_global_load_lds((const unsigned*)((const char*)(gbase) + (voff)[_i]), (PG8_LAS unsigned*)(lds + (bufoff) + ldsw + _i * 8192), 16, 0, 0); } while (0)
; #define PG8_LDA(dst, b, h) do { _Pragma("unroll") for (int m = 0; m < 4; ++m) _Pragma("unroll") for (int k = 0; k < 2; ++k) dst[m][k] = *(const PG8_LAS bf16x8*)(lds + PG8_SA(b, h) + aoff + m * 2048 + k * 1024); } while (0)
; #define PG8_LDB(dst, b, h) do { _Pragma("unroll") for (int n = 0; n < 2; ++n) _Pragma("unroll") for (int k = 0; k < 2; ++k) dst[n][k] = *(const PG8_LAS bf16x8*)(lds + PG8_SB(b, h) + boff + n * 2048 + k * 1024); } while (0)
; #define PG8_MMA(ai, bj, At, Bt) do { __builtin_amdgcn_s_setprio(1); _Pragma("unroll") for (int m = 0; m < 4; ++m) _Pragma("unroll") for (int n = 0; n < 2; ++n) _Pragma("unroll") for (int k = 0; k < 2; ++k) \
;         acc[ai][bj][m][n] = __builtin_amdgcn_mfma_f32_16x16x32_bf16(Bt[n][k], At[m][k], acc[ai][bj][m][n], 0, 0, 0); __builtin_amdgcn_s_setprio(0); } while (0)
; #define PG8_WAIT_V(n) asm volatile("s_waitcnt vmcnt(" #n ")" ::: "memory")
; #define PG8_WAIT_L(n) asm volatile("s_waitcnt lgkmcnt(" #n ")" ::: "memory")
; #define PG8_BAR __builtin_amdgcn_s_barrier()
; #define PG8_SCHED __builtin_amdgcn_sched_barrier(0)
; template <class Epi, class Sched, bool ALIGN_EPI = false, bool SP2 = false>
; __device__ __forceinline__ void gemm_phase(PG8_LAS unsigned char* lds, const Gemm g, const Sched& S, const Epi& E) {
;     ...
;             PG8_LDB(B0, 1, 0); PG8_LDB(B1, 1, 1); PG8_SCHED; PG8_LDA(At, 1, 0); PG8_STAGE(PG8_SA(0, 1), a2 + hstep, voffA);
;             PG8_WAIT_V(8); PG8_WAIT_L(0); PG8_BAR; PG8_MMA(0, 0, At, B0); PG8_MMA(0, 1, At, B1); PG8_BAR; PG8_SCHED;
;             PG8_LDA(At, 1, 1); PG8_STAGE(PG8_SB(1, 0), b3, voffB); PG8_STAGE(PG8_SB(1, 1), b3 + hstep, voffB); PG8_STAGE(PG8_SA(1, 0), a3, voffA);
;             PG8_WAIT_V(8); PG8_WAIT_L(0); PG8_BAR; PG8_MMA(1, 0, At, B0); PG8_MMA(1, 1, At, B1); PG8_BAR; PG8_SCHED;
	s_add_i32 s16, s18, s41
	v_lshl_add_u64 v[198:199], v[198:199], 0, s[20:21]
	s_mov_b32 m0, s16
	ds_read_b128 v[190:193], v210 offset:49152
	ds_read_b128 v[194:197], v210 offset:50176
	ds_read_b128 v[212:215], v210 offset:51200
	ds_read_b128 v[216:219], v210 offset:52224
	ds_read_b128 v[220:223], v210 offset:53248
	ds_read_b128 v[224:227], v210 offset:54272
	ds_read_b128 v[228:231], v210 offset:55296
	ds_read_b128 v[232:235], v210 offset:56320
	global_load_lds_dwordx4 v[198:199], off
	v_lshl_add_u64 v[198:199], v[236:237], 0, s[20:21]
	s_add_i32 m0, s16, 0x2000
	s_add_i32 s16, s33, s41
	global_load_lds_dwordx4 v[198:199], off
	v_lshl_add_u64 v[198:199], v[238:239], 0, s[20:21]
	s_mov_b32 m0, s16
	s_nop 0
	global_load_lds_dwordx4 v[198:199], off
	v_lshl_add_u64 v[198:199], v[240:241], 0, s[20:21]
	s_add_i32 m0, s16, 0x2000
	s_nop 0
	global_load_lds_dwordx4 v[198:199], off
	v_lshl_add_u64 v[198:199], v[242:243], 0, s[20:21]
	v_lshl_add_u64 v[244:245], v[244:245], 0, s[20:21]
	s_waitcnt vmcnt(6)
	s_waitcnt lgkmcnt(0)
	s_barrier
	s_setprio 1
	s_waitcnt lgkmcnt(0)
	v_mfma_f32_16x16x32_bf16 v[68:71], v[144:147], v[190:193], v[68:71]
	v_mfma_f32_16x16x32_bf16 v[64:67], v[152:155], v[190:193], v[64:67]
	v_mfma_f32_16x16x32_bf16 v[52:55], v[144:147], v[212:215], v[52:55]
	s_mov_b32 m0, s56
	v_mfma_f32_16x16x32_bf16 v[48:51], v[152:155], v[212:215], v[48:51]
	global_load_lds_dwordx4 v[198:199], off
	v_mfma_f32_16x16x32_bf16 v[36:39], v[144:147], v[220:223], v[36:39]
	v_mfma_f32_16x16x32_bf16 v[32:35], v[152:155], v[220:223], v[32:35]
	v_mfma_f32_16x16x32_bf16 v[20:23], v[144:147], v[228:231], v[20:23]
	v_mfma_f32_16x16x32_bf16 v[16:19], v[152:155], v[228:231], v[16:19]
	v_mfma_f32_16x16x32_bf16 v[68:71], v[148:151], v[194:197], v[68:71]
	v_mfma_f32_16x16x32_bf16 v[64:67], v[156:159], v[194:197], v[64:67]
	v_mfma_f32_16x16x32_bf16 v[52:55], v[148:151], v[216:219], v[52:55]
	s_mov_b32 m0, s57
	v_mfma_f32_16x16x32_bf16 v[48:51], v[156:159], v[216:219], v[48:51]
	global_load_lds_dwordx4 v[244:245], off
	v_mfma_f32_16x16x32_bf16 v[36:39], v[148:151], v[224:227], v[36:39]
	v_mfma_f32_16x16x32_bf16 v[32:35], v[156:159], v[224:227], v[32:35]
	v_mfma_f32_16x16x32_bf16 v[20:23], v[148:151], v[232:235], v[20:23]
	v_mfma_f32_16x16x32_bf16 v[16:19], v[156:159], v[232:235], v[16:19]
	s_setprio 0
	s_setprio 1
	v_mfma_f32_16x16x32_bf16 v[60:63], v[160:163], v[190:193], v[60:63]
	v_mfma_f32_16x16x32_bf16 v[56:59], v[182:185], v[190:193], v[56:59]
	v_mfma_f32_16x16x32_bf16 v[44:47], v[160:163], v[212:215], v[44:47]
	v_mfma_f32_16x16x32_bf16 v[40:43], v[182:185], v[212:215], v[40:43]
	v_mfma_f32_16x16x32_bf16 v[28:31], v[160:163], v[220:223], v[28:31]
	v_mfma_f32_16x16x32_bf16 v[24:27], v[182:185], v[220:223], v[24:27]
	v_mfma_f32_16x16x32_bf16 v[12:15], v[160:163], v[228:231], v[12:15]
	v_mfma_f32_16x16x32_bf16 v[8:11], v[182:185], v[228:231], v[8:11]
	v_mfma_f32_16x16x32_bf16 v[60:63], v[178:181], v[194:197], v[60:63]
	v_mfma_f32_16x16x32_bf16 v[56:59], v[186:189], v[194:197], v[56:59]
	v_mfma_f32_16x16x32_bf16 v[44:47], v[178:181], v[216:219], v[44:47]
	v_mfma_f32_16x16x32_bf16 v[40:43], v[186:189], v[216:219], v[40:43]
	v_mfma_f32_16x16x32_bf16 v[28:31], v[178:181], v[224:227], v[28:31]
	v_mfma_f32_16x16x32_bf16 v[24:27], v[186:189], v[224:227], v[24:27]
	v_mfma_f32_16x16x32_bf16 v[12:15], v[178:181], v[232:235], v[12:15]
	v_mfma_f32_16x16x32_bf16 v[8:11], v[186:189], v[232:235], v[8:11]
	s_setprio 0
	s_barrier
	s_add_u32 s24, s24, 0x100
	s_addc_u32 s25, s25, 0
	s_add_u32 s23, s23, 0x100
	s_addc_u32 s35, s35, 0
	s_cmp_ge_u32 s36, s59
	s_mov_b32 s28, s36
	s_cbranch_scc0 .LBB0_203
	s_and_b64 vcc, exec, s[46:47]
	s_cbranch_vccz .LBB0_206
	s_barrier
	s_setprio 1

; #define PG8_STAGE(bufoff, gbase, voff) do { _Pragma("unroll") for (int _i = 0; _i < 2; ++_i) \
;         __builtin_amdgcn_global_load_lds((const unsigned*)((const char*)(gbase) + (voff)[_i]), (PG8_LAS unsigned*)(lds + (bufoff) + ldsw + _i * 8192), 16, 0, 0); } while (0)
; #define PG8_LDA(dst, b, h) do { _Pragma("unroll") for (int m = 0; m < 4; ++m) _Pragma("unroll") for (int k = 0; k < 2; ++k) dst[m][k] = *(const PG8_LAS bf16x8*)(lds + PG8_SA(b, h) + aoff + m * 2048 + k * 1024); } while (0)
; #define PG8_LDB(dst, b, h) do { _Pragma("unroll") for (int n = 0; n < 2; ++n) _Pragma("unroll") for (int k = 0; k < 2; ++k) dst[n][k] = *(const PG8_LAS bf16x8*)(lds + PG8_SB(b, h) + boff + n * 2048 + k * 1024); } while (0)
; #define PG8_MMA(ai, bj, At, Bt) do { __builtin_amdgcn_s_setprio(1); _Pragma("unroll") for (int m = 0; m < 4; ++m) _Pragma("unroll") for (int n = 0; n < 2; ++n) _Pragma("unroll") for (int k = 0; k < 2; ++k) \
;         acc[ai][bj][m][n] = __builtin_amdgcn_mfma_f32_16x16x32_bf16(Bt[n][k], At[m][k], acc[ai][bj][m][n], 0, 0, 0); __builtin_amdgcn_s_setprio(0); } while (0)
; #define PG8_WAIT_V(n) asm volatile("s_waitcnt vmcnt(" #n ")" ::: "memory")
; #define PG8_BAR __builtin_amdgcn_s_barrier()
; template <class Epi, class Sched, bool ALIGN_EPI = false, bool SP2 = false>
; __device__ __forceinline__ void gemm_phase(PG8_LAS unsigned char* lds, const Gemm g, const Sched& S, const Epi& E) {
;     ...
;         for (int t = 0; t < nt; t += 2) {
;             const bool last = (t == nt - 2);
;             const char* a1 = cA + (size_t)(t + 1) * kstep;
;             const char* a2 = last ? nA : cA + (size_t)(t + 2) * kstep; const char* b2 = last ? nB : cB + (size_t)(t + 2) * kstep;
;             const char* a3 = a2 + kstep; const char* b3 = b2 + kstep;
;             if (last && has_next) S.a_ready(nxt);
;             if constexpr (SP2) {
;             PG8_LDB(B0, 0, 0); PG8_LDB(B1, 0, 1); PG8_SCHED; PG8_LDA(At, 0, 0); PG8_STAGE(PG8_SA(1, 1), a1 + hstep, voffA);
;             PG8_WAIT_V(8); PG8_WAIT_L(0); PG8_BAR; PG8_MMA(0, 0, At, B0); PG8_MMA(0, 1, At, B1); PG8_BAR; PG8_SCHED;
;             PG8_LDA(At, 0, 1); PG8_STAGE(PG8_SB(0, 0), b2, voffB); PG8_STAGE(PG8_SB(0, 1), b2 + hstep, voffB); PG8_STAGE(PG8_SA(0, 0), a2, voffA);
;             PG8_WAIT_V(8); PG8_WAIT_L(0); PG8_BAR; PG8_MMA(1, 0, At, B0); PG8_MMA(1, 1, At, B1); PG8_BAR; PG8_SCHED;
.LBB0_257:
	s_add_u32 s16, s8, 0xfffc0080
	s_addc_u32 s17, s9, -1
	s_add_i32 s18, 0, 0x10000
	s_cmp_eq_u32 s55, 12
	s_cselect_b32 s43, s14, s17
	s_cselect_b32 s42, s15, s16
	v_add_u32_e32 v0, s18, v210
	s_cselect_b32 s41, s13, s54
	s_cselect_b32 s40, s25, s53
	s_add_i32 s19, 0, 0x14000
	ds_read_b128 v[104:107], v0
	ds_read_b128 v[140:143], v0 offset:1024
	ds_read_b128 v[144:147], v0 offset:2048
	ds_read_b128 v[148:151], v0 offset:3072
	v_add_u32_e32 v0, s19, v210
	ds_read_b128 v[152:155], v0
	ds_read_b128 v[156:159], v0 offset:1024
	ds_read_b128 v[160:163], v0 offset:2048
	ds_read_b128 v[192:195], v0 offset:3072
	v_lshl_add_u64 v[2:3], s[8:9], 0, v[188:189]
	s_add_i32 m0, s44, 0xc000
	ds_read_b128 v[196:199], v212
	ds_read_b128 v[214:217], v212 offset:1024
	ds_read_b128 v[218:221], v212 offset:2048
	ds_read_b128 v[222:225], v212 offset:3072
	ds_read_b128 v[226:229], v212 offset:4096
	ds_read_b128 v[230:233], v212 offset:5120
	ds_read_b128 v[234:237], v212 offset:6144
	ds_read_b128 v[238:241], v212 offset:7168
	global_load_lds_dwordx4 v[2:3], off
	v_lshl_add_u64 v[2:3], s[8:9], 0, v[190:191]
	s_add_i32 m0, s44, 0xe000
	s_nop 0
	global_load_lds_dwordx4 v[2:3], off
	s_waitcnt vmcnt(8)
	s_waitcnt lgkmcnt(0)
	s_barrier
	s_setprio 1
	s_waitcnt lgkmcnt(0)
	v_mfma_f32_16x16x32_bf16 v[136:139], v[104:107], v[196:199], v[136:139]
	v_mfma_f32_16x16x32_bf16 v[128:131], v[144:147], v[196:199], v[128:131]
	v_mfma_f32_16x16x32_bf16 v[120:123], v[104:107], v[218:221], v[120:123]
	v_mfma_f32_16x16x32_bf16 v[112:115], v[144:147], v[218:221], v[112:115]
	v_mfma_f32_16x16x32_bf16 v[100:103], v[104:107], v[226:229], v[100:103]
	v_mfma_f32_16x16x32_bf16 v[92:95], v[144:147], v[226:229], v[92:95]
	v_mfma_f32_16x16x32_bf16 v[84:87], v[104:107], v[234:237], v[84:87]
	v_mfma_f32_16x16x32_bf16 v[76:79], v[144:147], v[234:237], v[76:79]
	v_mfma_f32_16x16x32_bf16 v[136:139], v[140:143], v[214:217], v[136:139]
	v_mfma_f32_16x16x32_bf16 v[128:131], v[148:151], v[214:217], v[128:131]
	v_mfma_f32_16x16x32_bf16 v[120:123], v[140:143], v[222:225], v[120:123]
	v_mfma_f32_16x16x32_bf16 v[112:115], v[148:151], v[222:225], v[112:115]
	v_mfma_f32_16x16x32_bf16 v[100:103], v[140:143], v[230:233], v[100:103]
	v_mfma_f32_16x16x32_bf16 v[92:95], v[148:151], v[230:233], v[92:95]
	v_mfma_f32_16x16x32_bf16 v[84:87], v[140:143], v[238:241], v[84:87]
	v_mfma_f32_16x16x32_bf16 v[76:79], v[148:151], v[238:241], v[76:79]
	s_setprio 0
	s_setprio 1
	v_mfma_f32_16x16x32_bf16 v[132:135], v[152:155], v[196:199], v[132:135]
	v_mfma_f32_16x16x32_bf16 v[124:127], v[160:163], v[196:199], v[124:127]
	v_mfma_f32_16x16x32_bf16 v[116:119], v[152:155], v[218:221], v[116:119]
	v_mfma_f32_16x16x32_bf16 v[108:111], v[160:163], v[218:221], v[108:111]
	v_mfma_f32_16x16x32_bf16 v[96:99], v[152:155], v[226:229], v[96:99]
	v_mfma_f32_16x16x32_bf16 v[88:91], v[160:163], v[226:229], v[88:91]
	v_mfma_f32_16x16x32_bf16 v[80:83], v[152:155], v[234:237], v[80:83]
	v_mfma_f32_16x16x32_bf16 v[72:75], v[160:163], v[234:237], v[72:75]
	v_mfma_f32_16x16x32_bf16 v[132:135], v[156:159], v[214:217], v[132:135]
	v_mfma_f32_16x16x32_bf16 v[124:127], v[192:195], v[214:217], v[124:127]
	v_mfma_f32_16x16x32_bf16 v[116:119], v[156:159], v[222:225], v[116:119]
	v_mfma_f32_16x16x32_bf16 v[108:111], v[192:195], v[222:225], v[108:111]
	v_mfma_f32_16x16x32_bf16 v[96:99], v[156:159], v[230:233], v[96:99]
	v_mfma_f32_16x16x32_bf16 v[88:91], v[192:195], v[230:233], v[88:91]
	v_mfma_f32_16x16x32_bf16 v[80:83], v[156:159], v[238:241], v[80:83]
	v_mfma_f32_16x16x32_bf16 v[72:75], v[192:195], v[238:241], v[72:75]
	s_setprio 0
	s_barrier
	s_add_i32 s16, s18, s36
	v_lshl_add_u64 v[2:3], s[40:41], 0, v[182:183]
	s_mov_b32 m0, s16
	ds_read_b128 v[196:199], v212 offset:16384
	ds_read_b128 v[214:217], v212 offset:17408
	ds_read_b128 v[218:221], v212 offset:18432
	ds_read_b128 v[222:225], v212 offset:19456
	ds_read_b128 v[226:229], v212 offset:20480
	ds_read_b128 v[230:233], v212 offset:21504
	ds_read_b128 v[234:237], v212 offset:22528
	ds_read_b128 v[238:241], v212 offset:23552
	global_load_lds_dwordx4 v[2:3], off
	s_add_i32 m0, s16, 0x2000
	s_add_u32 s16, s40, 0x40000
	v_lshl_add_u64 v[200:201], s[40:41], 0, v[178:179]
	s_addc_u32 s17, s41, 0
	s_add_i32 s18, s19, s36
	global_load_lds_dwordx4 v[200:201], off
	v_lshl_add_u64 v[242:243], s[16:17], 0, v[182:183]
	s_mov_b32 m0, s18
	v_lshl_add_u64 v[244:245], s[42:43], 0, v[180:181]
	global_load_lds_dwordx4 v[242:243], off
	v_lshl_add_u64 v[242:243], s[16:17], 0, v[178:179]
	s_add_i32 m0, s18, 0x2000
	s_nop 0
	global_load_lds_dwordx4 v[242:243], off
	v_lshl_add_u64 v[242:243], s[42:43], 0, v[184:185]
	s_waitcnt vmcnt(6)
	s_waitcnt lgkmcnt(0)
	s_barrier
; #define PG8_STAGE(bufoff, gbase, voff) do { _Pragma("unroll") for (int _i = 0; _i < 2; ++_i) \
;         __builtin_amdgcn_global_load_lds((const unsigned*)((const char*)(gbase) + (voff)[_i]), (PG8_LAS unsigned*)(lds + (bufoff) + ldsw + _i * 8192), 16, 0, 0); } while (0)
; #define PG8_LDA(dst, b, h) do { _Pragma("unroll") for (int m = 0; m < 4; ++m) _Pragma("unroll") for (int k = 0; k < 2; ++k) dst[m][k] = *(const PG8_LAS bf16x8*)(lds + PG8_SA(b, h) + aoff + m * 2048 + k * 1024); } while (0)
; #define PG8_LDB(dst, b, h) do { _Pragma("unroll") for (int n = 0; n < 2; ++n) _Pragma("unroll") for (int k = 0; k < 2; ++k) dst[n][k] = *(const PG8_LAS bf16x8*)(lds + PG8_SB(b, h) + boff + n * 2048 + k * 1024); } while (0)
; #define PG8_MMA(ai, bj, At, Bt) do { __builtin_amdgcn_s_setprio(1); _Pragma("unroll") for (int m = 0; m < 4; ++m) _Pragma("unroll") for (int n = 0; n < 2; ++n) _Pragma("unroll") for (int k = 0; k < 2; ++k) \
;         acc[ai][bj][m][n] = __builtin_amdgcn_mfma_f32_16x16x32_bf16(Bt[n][k], At[m][k], acc[ai][bj][m][n], 0, 0, 0); __builtin_amdgcn_s_setprio(0); } while (0)
; #define PG8_WAIT_V(n) asm volatile("s_waitcnt vmcnt(" #n ")" ::: "memory")
; #define PG8_WAIT_L(n) asm volatile("s_waitcnt lgkmcnt(" #n ")" ::: "memory")
; #define PG8_BAR __builtin_amdgcn_s_barrier()
; #define PG8_SCHED __builtin_amdgcn_sched_barrier(0)
; template <class Epi, class Sched, bool ALIGN_EPI = false, bool SP2 = false>
; __device__ __forceinline__ void gemm_phase(PG8_LAS unsigned char* lds, const Gemm g, const Sched& S, const Epi& E) {
;     ...
;             PG8_WAIT_V(8); PG8_WAIT_L(0); PG8_BAR; PG8_MMA(0, 0, At, B0); PG8_MMA(0, 1, At, B1); PG8_BAR; PG8_SCHED;
;             PG8_LDA(At, 0, 1); PG8_STAGE(PG8_SB(0, 0), b2, voffB); PG8_STAGE(PG8_SB(0, 1), b2 + hstep, voffB); PG8_STAGE(PG8_SA(0, 0), a2, voffA);
;             PG8_WAIT_V(8); PG8_WAIT_L(0); PG8_BAR; PG8_MMA(1, 0, At, B0); PG8_MMA(1, 1, At, B1); PG8_BAR; PG8_SCHED;
;             PG8_LDB(B0, 1, 0); PG8_LDB(B1, 1, 1); PG8_SCHED; PG8_LDA(At, 1, 0); PG8_STAGE(PG8_SA(0, 1), a2 + hstep, voffA);
;             PG8_WAIT_V(8); PG8_WAIT_L(0); PG8_BAR; PG8_MMA(0, 0, At, B0); PG8_MMA(0, 1, At, B1); PG8_BAR; PG8_SCHED;
	s_setprio 1
	s_waitcnt lgkmcnt(0)
	v_mfma_f32_16x16x32_bf16 v[68:71], v[104:107], v[196:199], v[68:71]
	v_mfma_f32_16x16x32_bf16 v[60:63], v[144:147], v[196:199], v[60:63]
	v_mfma_f32_16x16x32_bf16 v[52:55], v[104:107], v[218:221], v[52:55]
	s_mov_b32 m0, s44
	v_mfma_f32_16x16x32_bf16 v[44:47], v[144:147], v[218:221], v[44:47]
	global_load_lds_dwordx4 v[242:243], off
	v_mfma_f32_16x16x32_bf16 v[36:39], v[104:107], v[226:229], v[36:39]
	v_mfma_f32_16x16x32_bf16 v[28:31], v[144:147], v[226:229], v[28:31]
	v_mfma_f32_16x16x32_bf16 v[20:23], v[104:107], v[234:237], v[20:23]
	v_mfma_f32_16x16x32_bf16 v[12:15], v[144:147], v[234:237], v[12:15]
	v_mfma_f32_16x16x32_bf16 v[68:71], v[140:143], v[214:217], v[68:71]
	v_mfma_f32_16x16x32_bf16 v[60:63], v[148:151], v[214:217], v[60:63]
	v_mfma_f32_16x16x32_bf16 v[52:55], v[140:143], v[222:225], v[52:55]
	s_mov_b32 m0, s45
	v_mfma_f32_16x16x32_bf16 v[44:47], v[148:151], v[222:225], v[44:47]
	global_load_lds_dwordx4 v[244:245], off
	v_mfma_f32_16x16x32_bf16 v[36:39], v[140:143], v[230:233], v[36:39]
	v_mfma_f32_16x16x32_bf16 v[28:31], v[148:151], v[230:233], v[28:31]
	v_mfma_f32_16x16x32_bf16 v[20:23], v[140:143], v[238:241], v[20:23]
	v_mfma_f32_16x16x32_bf16 v[12:15], v[148:151], v[238:241], v[12:15]
	s_setprio 0
	s_setprio 1
	v_mfma_f32_16x16x32_bf16 v[64:67], v[152:155], v[196:199], v[64:67]
	v_mfma_f32_16x16x32_bf16 v[56:59], v[160:163], v[196:199], v[56:59]
	v_mfma_f32_16x16x32_bf16 v[48:51], v[152:155], v[218:221], v[48:51]
	v_mfma_f32_16x16x32_bf16 v[40:43], v[160:163], v[218:221], v[40:43]
	v_mfma_f32_16x16x32_bf16 v[32:35], v[152:155], v[226:229], v[32:35]
	v_mfma_f32_16x16x32_bf16 v[24:27], v[160:163], v[226:229], v[24:27]
	v_mfma_f32_16x16x32_bf16 v[16:19], v[152:155], v[234:237], v[16:19]
	v_mfma_f32_16x16x32_bf16 v[8:11], v[160:163], v[234:237], v[8:11]
	v_mfma_f32_16x16x32_bf16 v[64:67], v[156:159], v[214:217], v[64:67]
	v_mfma_f32_16x16x32_bf16 v[56:59], v[192:195], v[214:217], v[56:59]
	v_mfma_f32_16x16x32_bf16 v[48:51], v[156:159], v[222:225], v[48:51]
	v_mfma_f32_16x16x32_bf16 v[40:43], v[192:195], v[222:225], v[40:43]
	v_mfma_f32_16x16x32_bf16 v[32:35], v[156:159], v[230:233], v[32:35]
	v_mfma_f32_16x16x32_bf16 v[24:27], v[192:195], v[230:233], v[24:27]
	v_mfma_f32_16x16x32_bf16 v[16:19], v[156:159], v[238:241], v[16:19]
	v_mfma_f32_16x16x32_bf16 v[8:11], v[192:195], v[238:241], v[8:11]
	s_setprio 0
	s_barrier
	s_add_i32 s18, 0, 0x18000
	v_add_u32_e32 v0, s18, v210
	ds_read_b128 v[104:107], v0
	ds_read_b128 v[140:143], v0 offset:1024
	ds_read_b128 v[144:147], v0 offset:2048
	ds_read_b128 v[148:151], v0 offset:3072
	v_add_u32_e32 v0, s33, v210
	ds_read_b128 v[152:155], v0
	ds_read_b128 v[156:159], v0 offset:1024
	ds_read_b128 v[160:163], v0 offset:2048
	ds_read_b128 v[192:195], v0 offset:3072
	s_add_u32 s16, s42, 0x40000
	s_addc_u32 s17, s43, 0
	s_mov_b32 m0, s46
	v_lshl_add_u64 v[246:247], s[16:17], 0, v[184:185]
	ds_read_b128 v[196:199], v212 offset:32768
	ds_read_b128 v[214:217], v212 offset:33792
	ds_read_b128 v[218:221], v212 offset:34816
	ds_read_b128 v[222:225], v212 offset:35840
	ds_read_b128 v[226:229], v212 offset:36864
	ds_read_b128 v[230:233], v212 offset:37888
	ds_read_b128 v[234:237], v212 offset:38912
	ds_read_b128 v[238:241], v212 offset:39936
	global_load_lds_dwordx4 v[246:247], off
	v_lshl_add_u64 v[246:247], s[16:17], 0, v[180:181]
	s_mov_b32 m0, s47
	s_nop 0
	global_load_lds_dwordx4 v[246:247], off
	s_waitcnt vmcnt(8)
	s_waitcnt lgkmcnt(0)
	s_barrier
	s_setprio 1
	s_waitcnt lgkmcnt(0)
	v_mfma_f32_16x16x32_bf16 v[136:139], v[104:107], v[196:199], v[136:139]
	v_mfma_f32_16x16x32_bf16 v[128:131], v[144:147], v[196:199], v[128:131]
	v_mfma_f32_16x16x32_bf16 v[120:123], v[104:107], v[218:221], v[120:123]
	v_mfma_f32_16x16x32_bf16 v[112:115], v[144:147], v[218:221], v[112:115]
	v_mfma_f32_16x16x32_bf16 v[100:103], v[104:107], v[226:229], v[100:103]
	v_mfma_f32_16x16x32_bf16 v[92:95], v[144:147], v[226:229], v[92:95]
	v_mfma_f32_16x16x32_bf16 v[84:87], v[104:107], v[234:237], v[84:87]
	v_mfma_f32_16x16x32_bf16 v[76:79], v[144:147], v[234:237], v[76:79]
	v_mfma_f32_16x16x32_bf16 v[136:139], v[140:143], v[214:217], v[136:139]
	v_mfma_f32_16x16x32_bf16 v[128:131], v[148:151], v[214:217], v[128:131]
	v_mfma_f32_16x16x32_bf16 v[120:123], v[140:143], v[222:225], v[120:123]
	v_mfma_f32_16x16x32_bf16 v[112:115], v[148:151], v[222:225], v[112:115]
	v_mfma_f32_16x16x32_bf16 v[100:103], v[140:143], v[230:233], v[100:103]
	v_mfma_f32_16x16x32_bf16 v[92:95], v[148:151], v[230:233], v[92:95]
	v_mfma_f32_16x16x32_bf16 v[84:87], v[140:143], v[238:241], v[84:87]
	v_mfma_f32_16x16x32_bf16 v[76:79], v[148:151], v[238:241], v[76:79]
	s_setprio 0
	s_setprio 1
	v_mfma_f32_16x16x32_bf16 v[132:135], v[152:155], v[196:199], v[132:135]
	v_mfma_f32_16x16x32_bf16 v[124:127], v[160:163], v[196:199], v[124:127]
	v_mfma_f32_16x16x32_bf16 v[116:119], v[152:155], v[218:221], v[116:119]
	v_mfma_f32_16x16x32_bf16 v[108:111], v[160:163], v[218:221], v[108:111]
	v_mfma_f32_16x16x32_bf16 v[96:99], v[152:155], v[226:229], v[96:99]
	v_mfma_f32_16x16x32_bf16 v[88:91], v[160:163], v[226:229], v[88:91]
	v_mfma_f32_16x16x32_bf16 v[80:83], v[152:155], v[234:237], v[80:83]
	v_mfma_f32_16x16x32_bf16 v[72:75], v[160:163], v[234:237], v[72:75]
	v_mfma_f32_16x16x32_bf16 v[132:135], v[156:159], v[214:217], v[132:135]
	v_mfma_f32_16x16x32_bf16 v[124:127], v[192:195], v[214:217], v[124:127]
	v_mfma_f32_16x16x32_bf16 v[116:119], v[156:159], v[222:225], v[116:119]
	v_mfma_f32_16x16x32_bf16 v[108:111], v[192:195], v[222:225], v[108:111]
	v_mfma_f32_16x16x32_bf16 v[96:99], v[156:159], v[230:233], v[96:99]
	v_mfma_f32_16x16x32_bf16 v[88:91], v[192:195], v[230:233], v[88:91]
	v_mfma_f32_16x16x32_bf16 v[80:83], v[156:159], v[238:241], v[80:83]
	v_mfma_f32_16x16x32_bf16 v[72:75], v[192:195], v[238:241], v[72:75]
	s_setprio 0
	s_barrier
; #define PG8_STAGE(bufoff, gbase, voff) do { _Pragma("unroll") for (int _i = 0; _i < 2; ++_i) \
;         __builtin_amdgcn_global_load_lds((const unsigned*)((const char*)(gbase) + (voff)[_i]), (PG8_LAS unsigned*)(lds + (bufoff) + ldsw + _i * 8192), 16, 0, 0); } while (0)
; #define PG8_LDA(dst, b, h) do { _Pragma("unroll") for (int m = 0; m < 4; ++m) _Pragma("unroll") for (int k = 0; k < 2; ++k) dst[m][k] = *(const PG8_LAS bf16x8*)(lds + PG8_SA(b, h) + aoff + m * 2048 + k * 1024); } while (0)
; #define PG8_LDB(dst, b, h) do { _Pragma("unroll") for (int n = 0; n < 2; ++n) _Pragma("unroll") for (int k = 0; k < 2; ++k) dst[n][k] = *(const PG8_LAS bf16x8*)(lds + PG8_SB(b, h) + boff + n * 2048 + k * 1024); } while (0)
; #define PG8_MMA(ai, bj, At, Bt) do { __builtin_amdgcn_s_setprio(1); _Pragma("unroll") for (int m = 0; m < 4; ++m) _Pragma("unroll") for (int n = 0; n < 2; ++n) _Pragma("unroll") for (int k = 0; k < 2; ++k) \
;         acc[ai][bj][m][n] = __builtin_amdgcn_mfma_f32_16x16x32_bf16(Bt[n][k], At[m][k], acc[ai][bj][m][n], 0, 0, 0); __builtin_amdgcn_s_setprio(0); } while (0)
; #define PG8_WAIT_V(n) asm volatile("s_waitcnt vmcnt(" #n ")" ::: "memory")
; #define PG8_WAIT_L(n) asm volatile("s_waitcnt lgkmcnt(" #n ")" ::: "memory")
; #define PG8_BAR __builtin_amdgcn_s_barrier()
; #define PG8_SCHED __builtin_amdgcn_sched_barrier(0)
; template <class Epi, class Sched, bool ALIGN_EPI = false, bool SP2 = false>
; __device__ __forceinline__ void gemm_phase(PG8_LAS unsigned char* lds, const Gemm g, const Sched& S, const Epi& E) {
;     ...
;             PG8_LDB(B0, 1, 0); PG8_LDB(B1, 1, 1); PG8_SCHED; PG8_LDA(At, 1, 0); PG8_STAGE(PG8_SA(0, 1), a2 + hstep, voffA);
;             PG8_WAIT_V(8); PG8_WAIT_L(0); PG8_BAR; PG8_MMA(0, 0, At, B0); PG8_MMA(0, 1, At, B1); PG8_BAR; PG8_SCHED;
;             PG8_LDA(At, 1, 1); PG8_STAGE(PG8_SB(1, 0), b3, voffB); PG8_STAGE(PG8_SB(1, 1), b3 + hstep, voffB); PG8_STAGE(PG8_SA(1, 0), a3, voffA);
;             PG8_WAIT_V(8); PG8_WAIT_L(0); PG8_BAR; PG8_MMA(1, 0, At, B0); PG8_MMA(1, 1, At, B1); PG8_BAR; PG8_SCHED;
	s_add_i32 s16, s18, s36
	v_lshl_add_u64 v[2:3], v[2:3], 0, s[20:21]
	s_mov_b32 m0, s16
	ds_read_b128 v[196:199], v212 offset:49152
	ds_read_b128 v[214:217], v212 offset:50176
	ds_read_b128 v[218:221], v212 offset:51200
	ds_read_b128 v[222:225], v212 offset:52224
	ds_read_b128 v[226:229], v212 offset:53248
	ds_read_b128 v[230:233], v212 offset:54272
	ds_read_b128 v[234:237], v212 offset:55296
	ds_read_b128 v[238:241], v212 offset:56320
	global_load_lds_dwordx4 v[2:3], off
	s_add_i32 m0, s16, 0x2000
	s_add_u32 s16, s40, 0x40080
	v_lshl_add_u64 v[2:3], v[200:201], 0, s[20:21]
	s_addc_u32 s17, s41, 0
	s_add_i32 s18, s33, s36
	global_load_lds_dwordx4 v[2:3], off
	v_lshl_add_u64 v[2:3], s[16:17], 0, v[182:183]
	s_mov_b32 m0, s18
	s_nop 0
	global_load_lds_dwordx4 v[2:3], off
	v_lshl_add_u64 v[2:3], s[16:17], 0, v[178:179]
	s_add_i32 m0, s18, 0x2000
	s_nop 0
	global_load_lds_dwordx4 v[2:3], off
	v_lshl_add_u64 v[2:3], v[242:243], 0, s[20:21]
	v_lshl_add_u64 v[244:245], v[244:245], 0, s[20:21]
	s_waitcnt vmcnt(6)
	s_waitcnt lgkmcnt(0)
	s_barrier
	s_setprio 1
	s_waitcnt lgkmcnt(0)
	v_mfma_f32_16x16x32_bf16 v[68:71], v[104:107], v[196:199], v[68:71]
	v_mfma_f32_16x16x32_bf16 v[60:63], v[144:147], v[196:199], v[60:63]
	v_mfma_f32_16x16x32_bf16 v[52:55], v[104:107], v[218:221], v[52:55]
	s_mov_b32 m0, s48
	v_mfma_f32_16x16x32_bf16 v[44:47], v[144:147], v[218:221], v[44:47]
	global_load_lds_dwordx4 v[2:3], off
	v_mfma_f32_16x16x32_bf16 v[36:39], v[104:107], v[226:229], v[36:39]
	v_mfma_f32_16x16x32_bf16 v[28:31], v[144:147], v[226:229], v[28:31]
	v_mfma_f32_16x16x32_bf16 v[20:23], v[104:107], v[234:237], v[20:23]
	v_mfma_f32_16x16x32_bf16 v[12:15], v[144:147], v[234:237], v[12:15]
	v_mfma_f32_16x16x32_bf16 v[68:71], v[140:143], v[214:217], v[68:71]
	v_mfma_f32_16x16x32_bf16 v[60:63], v[148:151], v[214:217], v[60:63]
	v_mfma_f32_16x16x32_bf16 v[52:55], v[140:143], v[222:225], v[52:55]
	s_mov_b32 m0, s49
	v_mfma_f32_16x16x32_bf16 v[44:47], v[148:151], v[222:225], v[44:47]
	global_load_lds_dwordx4 v[244:245], off
	v_mfma_f32_16x16x32_bf16 v[36:39], v[140:143], v[230:233], v[36:39]
	v_mfma_f32_16x16x32_bf16 v[28:31], v[148:151], v[230:233], v[28:31]
	v_mfma_f32_16x16x32_bf16 v[20:23], v[140:143], v[238:241], v[20:23]
	v_mfma_f32_16x16x32_bf16 v[12:15], v[148:151], v[238:241], v[12:15]
	s_setprio 0
	s_setprio 1
	v_mfma_f32_16x16x32_bf16 v[64:67], v[152:155], v[196:199], v[64:67]
	v_mfma_f32_16x16x32_bf16 v[56:59], v[160:163], v[196:199], v[56:59]
	v_mfma_f32_16x16x32_bf16 v[48:51], v[152:155], v[218:221], v[48:51]
	v_mfma_f32_16x16x32_bf16 v[40:43], v[160:163], v[218:221], v[40:43]
	v_mfma_f32_16x16x32_bf16 v[32:35], v[152:155], v[226:229], v[32:35]
	v_mfma_f32_16x16x32_bf16 v[24:27], v[160:163], v[226:229], v[24:27]
	v_mfma_f32_16x16x32_bf16 v[16:19], v[152:155], v[234:237], v[16:19]
	v_mfma_f32_16x16x32_bf16 v[8:11], v[160:163], v[234:237], v[8:11]
	v_mfma_f32_16x16x32_bf16 v[64:67], v[156:159], v[214:217], v[64:67]
	v_mfma_f32_16x16x32_bf16 v[56:59], v[192:195], v[214:217], v[56:59]
	v_mfma_f32_16x16x32_bf16 v[48:51], v[156:159], v[222:225], v[48:51]
	v_mfma_f32_16x16x32_bf16 v[40:43], v[192:195], v[222:225], v[40:43]
	v_mfma_f32_16x16x32_bf16 v[32:35], v[156:159], v[230:233], v[32:35]
	v_mfma_f32_16x16x32_bf16 v[24:27], v[192:195], v[230:233], v[24:27]
	v_mfma_f32_16x16x32_bf16 v[16:19], v[156:159], v[238:241], v[16:19]
	v_mfma_f32_16x16x32_bf16 v[8:11], v[192:195], v[238:241], v[8:11]
	s_setprio 0
	s_barrier
	s_add_i32 s55, s55, 2
	s_add_u32 s8, s8, 0x100
	s_addc_u32 s9, s9, 0
	s_add_u32 s53, s53, 0x100
	s_addc_u32 s54, s54, 0
	s_cmp_gt_u32 s55, 13
	s_cbranch_scc0 .LBB0_257
	s_and_b64 vcc, exec, s[10:11]
	s_cbranch_vccz .LBB0_260
	s_barrier
	s_setprio 1
